# row passes A/B/C: per-row gain/scale/shift vector loads hoisted and issued together (were 8+8 serialised round trips per row); s5 unit prologue C-matrix loads batched
# speedup vs baseline: 1.0080x; 1.0080x over previous
; __device__ __forceinline__ unsigned pk2(float lo, float hi) { return pg8::cvt_pk_bf16(lo, hi); }
; __device__ __forceinline__ void row_pass(const RowPass& rp) {
;     ...
;     for (int row = gw; row < rp.nrows; row += NGW) {
;         const int v = (row < MLAT) ? (row >> 12) : 2;
;         const float* xs = (row < MLAT) ? rp.src_lat + (size_t)row * D : rp.src_ctx + (size_t)(row - MLAT) * D;
;         f32x4 x[8];
; #pragma unroll
;         for (int j = 0; j < 8; ++j) x[j] = *(const f32x4*)(xs + 4 * (lane + 64 * j));
;         if (rp.o) {
;             const bf16_t* orow = rp.o + (size_t)row * D; f32x4 ov[8]; float ss = 0.f;
; #pragma unroll
;             for (int j = 0; j < 8; ++j) { const u32x2 w2 = *(const u32x2*)(orow + 4 * (lane + 64 * j));
;                 ov[j] = (f32x4){__uint_as_float(w2.x << 16), __uint_as_float(w2.x & 0xffff0000u), __uint_as_float(w2.y << 16), __uint_as_float(w2.y & 0xffff0000u)};
;                 ss += ov[j][0] * ov[j][0] + ov[j][1] * ov[j][1] + ov[j][2] * ov[j][2] + ov[j][3] * ov[j][3]; }
;             const float rstd = rsqrtf(wave_sum(ss) * (1.f / D) + EPS);
; #pragma unroll
;             for (int j = 0; j < 8; ++j) { const int col = 4 * (lane + 64 * j); const f32x4 gp = *(const f32x4*)(rp.gpost + col); const f32x4 gt = *(const f32x4*)(rp.gatev + v * 12288 + col);
;                 x[j] = x[j] + gt * (ov[j] * rstd * gp); }
;         }
;         if (rp.dst_lat) { float* xd = (row < MLAT) ? rp.dst_lat + (size_t)row * D : rp.dst_ctx + (size_t)(row - MLAT) * D;
; #pragma unroll
;             for (int j = 0; j < 8; ++j) *(f32x4*)(xd + 4 * (lane + 64 * j)) = x[j]; }
;         if (rp.h) {
;             float ss = 0.f;
; #pragma unroll
;             for (int j = 0; j < 8; ++j) ss += x[j][0] * x[j][0] + x[j][1] * x[j][1] + x[j][2] * x[j][2] + x[j][3] * x[j][3];
;             const float rstd = rsqrtf(wave_sum(ss) * (1.f / D) + EPS);
;             bf16_t* hr = rp.h + (size_t)row * D;
; #pragma unroll
;             for (int j = 0; j < 8; ++j) { const int col = 4 * (lane + 64 * j); const f32x4 gp = *(const f32x4*)(rp.gpre + col); const f32x4 sh = *(const f32x4*)(rp.shv + v * 12288 + col); const f32x4 sc = *(const f32x4*)(rp.scv + v * 12288 + col);
;                 const f32x4 y = (x[j] * rstd * gp) * (sc + 1.f) + sh; u32x2 w; w.x = pk2(y[0], y[1]); w.y = pk2(y[2], y[3]); *(u32x2*)(hr + col) = w; }
.LBB0_97:
	v_add_u32_e32 v0, 0xffffe000, v12
	v_cmp_gt_i32_e32 vcc, s8, v12
	v_min_i32_e32 v4, 0x2000, v12
	v_ashrrev_i32_e32 v4, 12, v4
	v_cndmask_b32_e32 v1, 0, v13, vcc
	v_cndmask_b32_e32 v0, v0, v12, vcc
	v_cndmask_b32_e32 v3, v49, v50, vcc
	v_cndmask_b32_e32 v2, v51, v52, vcc
	v_lshlrev_b64 v[0:1], 13, v[0:1]
	v_mul_i32_i24_e32 v4, 0x3000, v4
	v_lshl_add_u64 v[0:1], v[2:3], 0, v[0:1]
	v_ashrrev_i32_e32 v5, 31, v4
	v_lshl_add_u64 v[36:37], v[0:1], 0, v[28:29]
	v_lshl_add_u64 v[2:3], v[0:1], 0, v[14:15]
	v_lshl_add_u64 v[6:7], v[0:1], 0, v[30:31]
	v_lshl_add_u64 v[38:39], v[0:1], 0, v[32:33]
	v_lshl_add_u64 v[0:1], v[0:1], 0, v[34:35]
	global_load_dwordx4 v[54:57], v[16:17], off
	v_lshlrev_b64 v[78:79], 2, v[4:5]
	global_load_dwordx4 v[58:61], v[36:37], off
	global_load_dwordx4 v[62:65], v[36:37], off offset:1024
	global_load_dwordx4 v[66:69], v[36:37], off offset:2048
	global_load_dwordx4 v[70:73], v[2:3], off
	global_load_dwordx4 v[8:11], v[6:7], off
	s_nop 0
	global_load_dwordx4 v[4:7], v[38:39], off
	s_nop 0
	global_load_dwordx4 v[0:3], v[0:1], off
	s_nop 0
	global_load_dwordx4 v[74:77], v[36:37], off offset:3072
	v_lshl_add_u64 v[36:37], s[2:3], 0, v[78:79]
	v_lshl_add_u64 v[38:39], s[68:69], 0, v[78:79]
	v_lshl_add_u64 v[86:87], v[36:37], 0, v[28:29]
	v_lshl_add_u64 v[88:89], v[38:39], 0, v[28:29]
	global_load_dwordx4 v[78:81], v[86:87], off
	global_load_dwordx4 v[82:85], v[88:89], off
	global_load_dwordx4 v[108:111], v[16:17], off offset:1024
	global_load_dwordx4 v[112:115], v[86:87], off offset:1024
	global_load_dwordx4 v[116:119], v[88:89], off offset:1024
	global_load_dwordx4 v[120:123], v[16:17], off offset:2048
	global_load_dwordx4 v[124:127], v[86:87], off offset:2048
	global_load_dwordx4 v[128:131], v[88:89], off offset:2048
	global_load_dwordx4 v[132:135], v[16:17], off offset:3072
	global_load_dwordx4 v[136:139], v[86:87], off offset:3072
	global_load_dwordx4 v[140:143], v[88:89], off offset:3072
	v_lshl_add_u64 v[192:193], v[36:37], 0, v[14:15]
	v_lshl_add_u64 v[194:195], v[38:39], 0, v[14:15]
	global_load_dwordx4 v[144:147], v[18:19], off
	global_load_dwordx4 v[148:151], v[192:193], off
	global_load_dwordx4 v[152:155], v[194:195], off
	v_lshl_add_u64 v[196:197], v[36:37], 0, v[30:31]
	v_lshl_add_u64 v[198:199], v[38:39], 0, v[30:31]
	global_load_dwordx4 v[156:159], v[20:21], off
	global_load_dwordx4 v[160:163], v[196:197], off
	global_load_dwordx4 v[164:167], v[198:199], off
	v_lshl_add_u64 v[200:201], v[36:37], 0, v[32:33]
	v_lshl_add_u64 v[202:203], v[38:39], 0, v[32:33]
	global_load_dwordx4 v[168:171], v[22:23], off
	global_load_dwordx4 v[172:175], v[200:201], off
	global_load_dwordx4 v[176:179], v[202:203], off
	v_lshl_add_u64 v[204:205], v[36:37], 0, v[34:35]
	v_lshl_add_u64 v[206:207], v[38:39], 0, v[34:35]
	global_load_dwordx4 v[180:183], v[24:25], off
	global_load_dwordx4 v[184:187], v[204:205], off
	global_load_dwordx4 v[208:211], v[206:207], off
	v_lshl_add_u64 v[12:13], v[12:13], 0, s[44:45]
	s_waitcnt vmcnt(30)
	v_mul_f32_e32 v40, v59, v59
	s_waitcnt vmcnt(29)
	v_mul_f32_e32 v53, v63, v63
	s_waitcnt vmcnt(28)
	v_mul_f32_e32 v106, v67, v67
	v_fmac_f32_e32 v40, v58, v58
	v_fmac_f32_e32 v53, v62, v62
	s_waitcnt vmcnt(27)
	v_mov_b32_e32 v92, v71
	s_waitcnt vmcnt(26)
	v_mov_b32_e32 v93, v9
	s_waitcnt vmcnt(23)
	v_mul_f32_e32 v107, v75, v75
	v_fmac_f32_e32 v106, v66, v66
	v_fmac_f32_e32 v40, v60, v60
	v_fmac_f32_e32 v53, v64, v64
	v_mov_b32_e32 v90, v70
	v_mov_b32_e32 v91, v8
	v_pk_mul_f32 v[92:93], v[92:93], v[92:93]
	v_fmac_f32_e32 v107, v74, v74
	v_fmac_f32_e32 v106, v68, v68
	v_fmac_f32_e32 v40, v61, v61
	v_fmac_f32_e32 v53, v65, v65
	v_mov_b32_e32 v96, v5
	v_mov_b32_e32 v97, v1
	v_mov_b32_e32 v98, v72
	v_mov_b32_e32 v99, v10
	v_pk_fma_f32 v[90:91], v[90:91], v[90:91], v[92:93]
	v_fmac_f32_e32 v107, v76, v76
	v_fmac_f32_e32 v106, v69, v69
	v_add_f32_e32 v40, v40, v53
	v_mov_b32_e32 v94, v4
	v_mov_b32_e32 v95, v0
	v_mov_b32_e32 v102, v73
	v_mov_b32_e32 v103, v11
	v_pk_mul_f32 v[96:97], v[96:97], v[96:97]
	v_pk_fma_f32 v[90:91], v[98:99], v[98:99], v[90:91]
	v_fmac_f32_e32 v107, v77, v77
	v_add_f32_e32 v40, v40, v106
	v_mov_b32_e32 v100, v6
	v_mov_b32_e32 v101, v2
	v_pk_fma_f32 v[92:93], v[94:95], v[94:95], v[96:97]
	v_pk_fma_f32 v[90:91], v[102:103], v[102:103], v[90:91]
	v_add_f32_e32 v40, v40, v107
	v_mov_b32_e32 v104, v7
	v_mov_b32_e32 v105, v3
	v_pk_fma_f32 v[92:93], v[100:101], v[100:101], v[92:93]
	v_add_f32_e32 v40, v40, v90
	v_pk_fma_f32 v[92:93], v[104:105], v[104:105], v[92:93]
	v_add_f32_e32 v40, v40, v91
	v_add_f32_e32 v40, v40, v92
	v_add_f32_e32 v40, v40, v93
	ds_bpermute_b32 v53, v42, v40
	s_waitcnt vmcnt(22)
	v_pk_add_f32 v[80:81], v[80:81], 1.0 op_sel_hi:[1,0]
	v_pk_add_f32 v[78:79], v[78:79], 1.0 op_sel_hi:[1,0]
	s_waitcnt lgkmcnt(0)
	v_add_f32_e32 v40, v40, v53
	ds_bpermute_b32 v53, v43, v40
	s_waitcnt lgkmcnt(0)
	v_add_f32_e32 v40, v40, v53
	ds_bpermute_b32 v53, v44, v40
	s_waitcnt lgkmcnt(0)
	v_add_f32_e32 v40, v40, v53
	ds_bpermute_b32 v53, v45, v40
	s_waitcnt lgkmcnt(0)
	v_add_f32_e32 v40, v40, v53
	ds_bpermute_b32 v53, v46, v40
	s_waitcnt lgkmcnt(0)
	v_add_f32_e32 v40, v40, v53
	ds_bpermute_b32 v53, v47, v40
	s_waitcnt lgkmcnt(0)
; __device__ __forceinline__ unsigned pk2(float lo, float hi) { return pg8::cvt_pk_bf16(lo, hi); }
; __device__ __forceinline__ void row_pass(const RowPass& rp) {
;     ...
;             const float rstd = rsqrtf(wave_sum(ss) * (1.f / D) + EPS);
;             bf16_t* hr = rp.h + (size_t)row * D;
; #pragma unroll
;             for (int j = 0; j < 8; ++j) { const int col = 4 * (lane + 64 * j); const f32x4 gp = *(const f32x4*)(rp.gpre + col); const f32x4 sh = *(const f32x4*)(rp.shv + v * 12288 + col); const f32x4 sc = *(const f32x4*)(rp.scv + v * 12288 + col);
;                 const f32x4 y = (x[j] * rstd * gp) * (sc + 1.f) + sh; u32x2 w; w.x = pk2(y[0], y[1]); w.y = pk2(y[2], y[3]); *(u32x2*)(hr + col) = w; }
	v_add_f32_e32 v40, v40, v53
	v_fmamk_f32 v40, v40, 0x3a000000, v48
	v_mul_f32_e32 v53, 0x4b800000, v40
	v_cmp_gt_f32_e32 vcc, s9, v40
	s_nop 1
	v_cndmask_b32_e32 v40, v40, v53, vcc
	v_rsq_f32_e32 v40, v40
	s_nop 0
	v_mul_f32_e32 v53, 0x45800000, v40
	v_cndmask_b32_e32 v40, v40, v53, vcc
	v_pk_mul_f32 v[60:61], v[60:61], v[40:41] op_sel_hi:[1,0]
	v_pk_mul_f32 v[58:59], v[58:59], v[40:41] op_sel_hi:[1,0]
	v_pk_mul_f32 v[56:57], v[56:57], v[60:61]
	v_pk_mul_f32 v[54:55], v[54:55], v[58:59]
	s_waitcnt vmcnt(21)
	v_pk_fma_f32 v[56:57], v[80:81], v[56:57], v[84:85]
	v_pk_fma_f32 v[54:55], v[78:79], v[54:55], v[82:83]
	v_pk_mul_f32 v[64:65], v[64:65], v[40:41] op_sel_hi:[1,0]
	v_cvt_pk_bf16_f32 v54, v54, v55
	v_cvt_pk_bf16_f32 v55, v56, v57
	global_store_dwordx2 v[26:27], v[54:55], off
	v_pk_mul_f32 v[62:63], v[62:63], v[40:41] op_sel_hi:[1,0]
	v_pk_mul_f32 v[68:69], v[68:69], v[40:41] op_sel_hi:[1,0]
	v_pk_mul_f32 v[66:67], v[66:67], v[40:41] op_sel_hi:[1,0]
	v_pk_mul_f32 v[76:77], v[76:77], v[40:41] op_sel_hi:[1,0]
	v_pk_mul_f32 v[74:75], v[74:75], v[40:41] op_sel_hi:[1,0]
	v_pk_mul_f32 v[72:73], v[72:73], v[40:41] op_sel_hi:[1,0]
	v_pk_mul_f32 v[70:71], v[70:71], v[40:41] op_sel_hi:[1,0]
	v_pk_mul_f32 v[10:11], v[10:11], v[40:41] op_sel_hi:[1,0]
	v_pk_mul_f32 v[8:9], v[8:9], v[40:41] op_sel_hi:[1,0]
	v_pk_mul_f32 v[6:7], v[6:7], v[40:41] op_sel_hi:[1,0]
	v_pk_mul_f32 v[4:5], v[4:5], v[40:41] op_sel_hi:[1,0]
	v_pk_mul_f32 v[2:3], v[2:3], v[40:41] op_sel_hi:[1,0]
	v_pk_mul_f32 v[0:1], v[0:1], v[40:41] op_sel_hi:[1,0]
	v_cmp_lt_i32_e32 vcc, s10, v12
	s_or_b64 s[6:7], vcc, s[6:7]
	s_waitcnt vmcnt(21)
	v_pk_mul_f32 v[54:55], v[108:109], v[62:63]
	v_pk_mul_f32 v[56:57], v[110:111], v[64:65]
	s_waitcnt vmcnt(20)
	v_pk_add_f32 v[60:61], v[114:115], 1.0 op_sel_hi:[1,0]
	v_pk_add_f32 v[58:59], v[112:113], 1.0 op_sel_hi:[1,0]
	s_waitcnt vmcnt(19)
	v_pk_fma_f32 v[56:57], v[60:61], v[56:57], v[118:119]
	v_pk_fma_f32 v[54:55], v[58:59], v[54:55], v[116:117]
	s_nop 0
	v_cvt_pk_bf16_f32 v54, v54, v55
	v_cvt_pk_bf16_f32 v55, v56, v57
	global_store_dwordx2 v[26:27], v[54:55], off offset:512
	s_waitcnt vmcnt(19)
	v_pk_mul_f32 v[212:213], v[120:121], v[66:67]
	v_pk_mul_f32 v[214:215], v[122:123], v[68:69]
	s_waitcnt vmcnt(18)
	v_pk_add_f32 v[218:219], v[126:127], 1.0 op_sel_hi:[1,0]
	v_pk_add_f32 v[216:217], v[124:125], 1.0 op_sel_hi:[1,0]
	s_waitcnt vmcnt(17)
	v_pk_fma_f32 v[214:215], v[218:219], v[214:215], v[130:131]
	v_pk_fma_f32 v[212:213], v[216:217], v[212:213], v[128:129]
	s_nop 0
	v_cvt_pk_bf16_f32 v212, v212, v213
	v_cvt_pk_bf16_f32 v213, v214, v215
	global_store_dwordx2 v[26:27], v[212:213], off offset:1024
	s_waitcnt vmcnt(17)
	v_pk_mul_f32 v[54:55], v[132:133], v[74:75]
	v_pk_mul_f32 v[56:57], v[134:135], v[76:77]
	s_waitcnt vmcnt(16)
	v_pk_add_f32 v[60:61], v[138:139], 1.0 op_sel_hi:[1,0]
	v_pk_add_f32 v[58:59], v[136:137], 1.0 op_sel_hi:[1,0]
	s_waitcnt vmcnt(15)
	v_pk_fma_f32 v[56:57], v[60:61], v[56:57], v[142:143]
	v_pk_fma_f32 v[54:55], v[58:59], v[54:55], v[140:141]
	s_nop 0
	v_cvt_pk_bf16_f32 v54, v54, v55
	v_cvt_pk_bf16_f32 v55, v56, v57
	global_store_dwordx2 v[26:27], v[54:55], off offset:1536
	s_waitcnt vmcnt(15)
	v_pk_mul_f32 v[212:213], v[144:145], v[70:71]
	v_pk_mul_f32 v[214:215], v[146:147], v[72:73]
	s_waitcnt vmcnt(14)
	v_pk_add_f32 v[218:219], v[150:151], 1.0 op_sel_hi:[1,0]
	v_pk_add_f32 v[216:217], v[148:149], 1.0 op_sel_hi:[1,0]
	s_waitcnt vmcnt(13)
	v_pk_fma_f32 v[214:215], v[218:219], v[214:215], v[154:155]
	v_pk_fma_f32 v[212:213], v[216:217], v[212:213], v[152:153]
	s_nop 0
	v_cvt_pk_bf16_f32 v212, v212, v213
	v_cvt_pk_bf16_f32 v213, v214, v215
	global_store_dwordx2 v[26:27], v[212:213], off offset:2048
	s_waitcnt vmcnt(13)
	v_pk_mul_f32 v[54:55], v[156:157], v[8:9]
	v_pk_mul_f32 v[56:57], v[158:159], v[10:11]
	s_waitcnt vmcnt(12)
	v_pk_add_f32 v[60:61], v[162:163], 1.0 op_sel_hi:[1,0]
	v_pk_add_f32 v[58:59], v[160:161], 1.0 op_sel_hi:[1,0]
	s_waitcnt vmcnt(11)
	v_pk_fma_f32 v[56:57], v[60:61], v[56:57], v[166:167]
	v_pk_fma_f32 v[54:55], v[58:59], v[54:55], v[164:165]
	s_nop 0
	v_cvt_pk_bf16_f32 v54, v54, v55
	v_cvt_pk_bf16_f32 v55, v56, v57
	global_store_dwordx2 v[26:27], v[54:55], off offset:2560
	s_waitcnt vmcnt(11)
	v_pk_mul_f32 v[212:213], v[168:169], v[4:5]
	v_pk_mul_f32 v[214:215], v[170:171], v[6:7]
	s_waitcnt vmcnt(10)
	v_pk_add_f32 v[218:219], v[174:175], 1.0 op_sel_hi:[1,0]
	v_pk_add_f32 v[216:217], v[172:173], 1.0 op_sel_hi:[1,0]
	s_waitcnt vmcnt(9)
	v_pk_fma_f32 v[214:215], v[218:219], v[214:215], v[178:179]
	v_pk_fma_f32 v[212:213], v[216:217], v[212:213], v[176:177]
	s_nop 0
	v_cvt_pk_bf16_f32 v212, v212, v213
	v_cvt_pk_bf16_f32 v213, v214, v215
	global_store_dwordx2 v[26:27], v[212:213], off offset:3072
	s_waitcnt vmcnt(9)
	v_pk_mul_f32 v[54:55], v[180:181], v[0:1]
	v_pk_mul_f32 v[56:57], v[182:183], v[2:3]
	s_waitcnt vmcnt(8)
	v_pk_add_f32 v[60:61], v[186:187], 1.0 op_sel_hi:[1,0]
	v_pk_add_f32 v[58:59], v[184:185], 1.0 op_sel_hi:[1,0]
	s_waitcnt vmcnt(7)
	v_pk_fma_f32 v[56:57], v[60:61], v[56:57], v[210:211]
	v_pk_fma_f32 v[54:55], v[58:59], v[54:55], v[208:209]
	s_nop 0
	v_cvt_pk_bf16_f32 v54, v54, v55
	v_cvt_pk_bf16_f32 v55, v56, v57
	global_store_dwordx2 v[26:27], v[54:55], off offset:3584
	v_lshl_add_u64 v[26:27], v[26:27], 0, s[4:5]
	s_andn2_b64 exec, exec, s[6:7]
	s_cbranch_execnz .LBB0_97

; __device__ __forceinline__ unsigned pk2(float lo, float hi) { return pg8::cvt_pk_bf16(lo, hi); }
; __device__ __forceinline__ void s5_phase(const Args& a, int l, unsigned char* ldsb) {
;     ...
;         bf16x8 cA[8];
; #pragma unroll
;         for (int kk = 0; kk < 8; ++kk) {
;             u32x4 t = (u32x4){0u, 0u, 0u, 0u};
;             if (r32 < 16) { const size_t ci_ = (((size_t)l * 64 + g) * 16 + r32) * 64 + 8 * kk + 4 * hi;
;                 const f32x4 c4 = *(const f32x4*)(a.in[24] + ci_), d4 = *(const f32x4*)(a.in[25] + ci_);
;                 t.x = pk2(c4[0], -d4[0]); t.y = pk2(c4[1], -d4[1]); t.z = pk2(c4[2], -d4[2]); t.w = pk2(c4[3], -d4[3]); }
;             cA[kk] = __builtin_bit_cast(bf16x8, t);
;         }
.LBB0_528:
	s_bfe_u32 s33, s72, 0x10006
	s_or_b32 s42, s33, s12
	s_and_b32 s74, s72, 63
	s_lshl_b32 s43, s42, 12
	s_lshl_b32 s42, s42, 6
	s_lshl_b32 s60, s74, 6
	s_or_b32 s76, s42, s74
	v_readlane_b32 s44, v252, 22
	s_or_b32 s61, s43, s60
	s_lshl_b64 s[42:43], s[76:77], 2
	v_readlane_b32 s54, v252, 32
	v_readlane_b32 s55, v252, 33
	s_add_u32 s42, s54, s42
	s_addc_u32 s43, s55, s43
	global_load_dword v38, v1, s[42:43]
	s_or_b32 s42, s60, s75
	v_or_b32_e32 v0, s61, v149
	v_lshlrev_b64 v[2:3], 2, v[0:1]
	v_or_b32_e32 v0, s42, v149
	v_lshlrev_b32_e32 v0, 4, v0
	v_lshlrev_b64 v[6:7], 2, v[0:1]
	v_readlane_b32 s50, v252, 28
	v_readlane_b32 s51, v252, 29
	v_readlane_b32 s52, v252, 30
	v_readlane_b32 s53, v252, 31
	v_lshl_add_u64 v[8:9], v[122:123], 0, v[6:7]
	v_lshl_add_u64 v[4:5], s[50:51], 0, v[2:3]
	v_lshl_add_u64 v[2:3], s[52:53], 0, v[2:3]
	v_lshl_add_u64 v[6:7], v[124:125], 0, v[6:7]
	global_load_dwordx4 v[18:21], v[8:9], off offset:16
	global_load_dwordx4 v[26:29], v[8:9], off
	global_load_dwordx4 v[22:25], v[6:7], off offset:16
	global_load_dwordx4 v[30:33], v[6:7], off
	global_load_dword v36, v[4:5], off
	global_load_dword v34, v[4:5], off offset:128
	global_load_dword v37, v[2:3], off
	global_load_dword v35, v[2:3], off offset:128
	v_or_b32_e32 v0, s42, v119
	v_lshlrev_b32_e32 v0, 4, v0
	v_lshlrev_b64 v[2:3], 2, v[0:1]
	v_lshl_add_u64 v[6:7], v[122:123], 0, v[2:3]
	v_lshl_add_u64 v[14:15], v[124:125], 0, v[2:3]
	global_load_dwordx4 v[2:5], v[6:7], off offset:16
	global_load_dwordx4 v[10:13], v[6:7], off
	s_nop 0
	global_load_dwordx4 v[6:9], v[14:15], off offset:16
	s_nop 0
	global_load_dwordx4 v[14:17], v[14:15], off
	v_readlane_b32 s45, v252, 23
	v_readlane_b32 s46, v252, 24
	v_readlane_b32 s47, v252, 25
	v_lshl_add_u32 v0, s74, 10, v218
	v_mov_b32_e32 v66, 0
	v_mov_b32_e32 v70, 0
	v_mov_b32_e32 v71, 0
	v_mov_b32_e32 v72, 0
	v_mov_b32_e32 v73, 0
	v_readlane_b32 s48, v252, 26
	v_readlane_b32 s49, v252, 27
	v_readlane_b32 s56, v252, 34
	v_readlane_b32 s57, v252, 35
	v_readlane_b32 s58, v252, 36
	v_readlane_b32 s59, v252, 37
	s_and_saveexec_b64 s[42:43], s[0:1]
	v_readlane_b32 s44, v252, 38
	v_readlane_b32 s45, v252, 39
	v_readlane_b32 s46, v252, 40
	v_readlane_b32 s47, v252, 41
	v_readlane_b32 s48, v252, 42
	v_readlane_b32 s49, v252, 43
	v_readlane_b32 s50, v252, 44
	v_readlane_b32 s51, v252, 45
	v_readlane_b32 s52, v252, 46
	v_readlane_b32 s53, v252, 47
	v_readlane_b32 s54, v252, 48
	v_readlane_b32 s55, v252, 49
	v_readlane_b32 s56, v252, 50
	v_readlane_b32 s57, v252, 51
	v_readlane_b32 s58, v252, 52
	v_readlane_b32 s59, v252, 53
	s_cbranch_execz .LBB0_530
	v_lshlrev_b64 v[44:45], 2, v[0:1]
	v_lshl_add_u64 v[40:41], s[46:47], 0, v[44:45]
	v_lshl_add_u64 v[44:45], s[44:45], 0, v[44:45]
	global_load_dwordx4 v[98:101], v[40:41], off
	global_load_dwordx4 v[152:155], v[44:45], off
	global_load_dwordx4 v[102:105], v[40:41], off offset:32
	global_load_dwordx4 v[156:159], v[44:45], off offset:32
	global_load_dwordx4 v[106:109], v[40:41], off offset:64
	global_load_dwordx4 v[160:163], v[44:45], off offset:64
	global_load_dwordx4 v[110:113], v[40:41], off offset:96
	global_load_dwordx4 v[164:167], v[44:45], off offset:96
	global_load_dwordx4 v[114:117], v[40:41], off offset:128
	global_load_dwordx4 v[168:171], v[44:45], off offset:128
	global_load_dwordx4 v[128:131], v[40:41], off offset:160
	global_load_dwordx4 v[172:175], v[44:45], off offset:160
	global_load_dwordx4 v[132:135], v[40:41], off offset:192
	global_load_dwordx4 v[176:179], v[44:45], off offset:192
	global_load_dwordx4 v[136:139], v[40:41], off offset:224
	global_load_dwordx4 v[180:183], v[44:45], off offset:224
	s_waitcnt vmcnt(15)
	v_xor_b32_e32 v39, 0x80000000, v98
	v_xor_b32_e32 v40, 0x80000000, v99
	v_xor_b32_e32 v41, 0x80000000, v100
	v_xor_b32_e32 v42, 0x80000000, v101
	s_waitcnt vmcnt(14)
	v_cvt_pk_bf16_f32 v70, v152, v39
	v_cvt_pk_bf16_f32 v71, v153, v40
	v_cvt_pk_bf16_f32 v72, v154, v41
	v_cvt_pk_bf16_f32 v73, v155, v42
; __device__ __forceinline__ unsigned pk2(float lo, float hi) { return pg8::cvt_pk_bf16(lo, hi); }
; __device__ __forceinline__ void s5_phase(const Args& a, int l, unsigned char* ldsb) {
;     ...
;         bf16x8 cA[8];
; #pragma unroll
;         for (int kk = 0; kk < 8; ++kk) {
;             u32x4 t = (u32x4){0u, 0u, 0u, 0u};
;             if (r32 < 16) { const size_t ci_ = (((size_t)l * 64 + g) * 16 + r32) * 64 + 8 * kk + 4 * hi;
;                 const f32x4 c4 = *(const f32x4*)(a.in[24] + ci_), d4 = *(const f32x4*)(a.in[25] + ci_);
;                 t.x = pk2(c4[0], -d4[0]); t.y = pk2(c4[1], -d4[1]); t.z = pk2(c4[2], -d4[2]); t.w = pk2(c4[3], -d4[3]); }
;             cA[kk] = __builtin_bit_cast(bf16x8, t);
;         }
.LBB0_530:
	s_or_b64 exec, exec, s[42:43]
	v_mov_b32_e32 v67, 0
	v_mov_b32_e32 v68, 0
	v_mov_b32_e32 v69, 0
	s_and_saveexec_b64 s[42:43], s[0:1]
	s_cbranch_execz .LBB0_532
	s_waitcnt vmcnt(13)
	v_xor_b32_e32 v39, 0x80000000, v102
	v_xor_b32_e32 v40, 0x80000000, v103
	v_xor_b32_e32 v41, 0x80000000, v104
	v_xor_b32_e32 v42, 0x80000000, v105
	s_waitcnt vmcnt(12)
	v_cvt_pk_bf16_f32 v66, v156, v39
	v_cvt_pk_bf16_f32 v67, v157, v40
	v_cvt_pk_bf16_f32 v68, v158, v41
	v_cvt_pk_bf16_f32 v69, v159, v42
.LBB0_532:
	s_or_b64 exec, exec, s[42:43]
	v_mov_b32_e32 v74, 0
	v_mov_b32_e32 v78, 0
	v_mov_b32_e32 v79, 0
	v_mov_b32_e32 v80, 0
	v_mov_b32_e32 v81, 0
	s_and_saveexec_b64 s[42:43], s[0:1]
	s_cbranch_execz .LBB0_534
	s_waitcnt vmcnt(11)
	v_xor_b32_e32 v39, 0x80000000, v106
	v_xor_b32_e32 v40, 0x80000000, v107
	v_xor_b32_e32 v41, 0x80000000, v108
	v_xor_b32_e32 v42, 0x80000000, v109
	s_waitcnt vmcnt(10)
	v_cvt_pk_bf16_f32 v78, v160, v39
	v_cvt_pk_bf16_f32 v79, v161, v40
	v_cvt_pk_bf16_f32 v80, v162, v41
	v_cvt_pk_bf16_f32 v81, v163, v42
.LBB0_534:
	s_or_b64 exec, exec, s[42:43]
	v_mov_b32_e32 v75, 0
	v_mov_b32_e32 v76, 0
	v_mov_b32_e32 v77, 0
	s_and_saveexec_b64 s[42:43], s[0:1]
	s_cbranch_execz .LBB0_536
	s_waitcnt vmcnt(9)
	v_xor_b32_e32 v39, 0x80000000, v110
	v_xor_b32_e32 v40, 0x80000000, v111
	v_xor_b32_e32 v41, 0x80000000, v112
	v_xor_b32_e32 v42, 0x80000000, v113
	s_waitcnt vmcnt(8)
	v_cvt_pk_bf16_f32 v74, v164, v39
	v_cvt_pk_bf16_f32 v75, v165, v40
	v_cvt_pk_bf16_f32 v76, v166, v41
	v_cvt_pk_bf16_f32 v77, v167, v42
.LBB0_536:
	s_or_b64 exec, exec, s[42:43]
	v_mov_b32_e32 v82, 0
	v_mov_b32_e32 v86, 0
	v_mov_b32_e32 v87, 0
	v_mov_b32_e32 v88, 0
	v_mov_b32_e32 v89, 0
	s_and_saveexec_b64 s[42:43], s[0:1]
	s_cbranch_execz .LBB0_538
	s_waitcnt vmcnt(7)
	v_xor_b32_e32 v39, 0x80000000, v114
	v_xor_b32_e32 v40, 0x80000000, v115
	v_xor_b32_e32 v41, 0x80000000, v116
	v_xor_b32_e32 v42, 0x80000000, v117
	s_waitcnt vmcnt(6)
	v_cvt_pk_bf16_f32 v86, v168, v39
	v_cvt_pk_bf16_f32 v87, v169, v40
	v_cvt_pk_bf16_f32 v88, v170, v41
	v_cvt_pk_bf16_f32 v89, v171, v42
.LBB0_538:
	s_or_b64 exec, exec, s[42:43]
	v_mov_b32_e32 v83, 0
	v_mov_b32_e32 v84, 0
	v_mov_b32_e32 v85, 0
	s_and_saveexec_b64 s[42:43], s[0:1]
	s_cbranch_execz .LBB0_540
	s_waitcnt vmcnt(5)
	v_xor_b32_e32 v39, 0x80000000, v128
	v_xor_b32_e32 v40, 0x80000000, v129
	v_xor_b32_e32 v41, 0x80000000, v130
	v_xor_b32_e32 v42, 0x80000000, v131
	s_waitcnt vmcnt(4)
	v_cvt_pk_bf16_f32 v82, v172, v39
	v_cvt_pk_bf16_f32 v83, v173, v40
	v_cvt_pk_bf16_f32 v84, v174, v41
	v_cvt_pk_bf16_f32 v85, v175, v42
.LBB0_540:
	s_or_b64 exec, exec, s[42:43]
	v_mov_b32_e32 v90, 0
	v_mov_b32_e32 v94, 0
	v_mov_b32_e32 v95, 0
	v_mov_b32_e32 v96, 0
	v_mov_b32_e32 v97, 0
	s_and_saveexec_b64 s[42:43], s[0:1]
	s_cbranch_execz .LBB0_542
	s_waitcnt vmcnt(3)
	v_xor_b32_e32 v39, 0x80000000, v132
	v_xor_b32_e32 v40, 0x80000000, v133
	v_xor_b32_e32 v41, 0x80000000, v134
	v_xor_b32_e32 v42, 0x80000000, v135
	s_waitcnt vmcnt(2)
	v_cvt_pk_bf16_f32 v94, v176, v39
	v_cvt_pk_bf16_f32 v95, v177, v40
	v_cvt_pk_bf16_f32 v96, v178, v41
	v_cvt_pk_bf16_f32 v97, v179, v42
.LBB0_542:
	s_or_b64 exec, exec, s[42:43]
	v_mov_b32_e32 v91, 0
	v_mov_b32_e32 v92, 0
	v_mov_b32_e32 v93, 0
	s_and_saveexec_b64 s[42:43], s[0:1]
	s_cbranch_execz .LBB0_544
	s_waitcnt vmcnt(1)
	v_xor_b32_e32 v0, 0x80000000, v136
	v_xor_b32_e32 v39, 0x80000000, v137
	v_xor_b32_e32 v40, 0x80000000, v138
	v_xor_b32_e32 v41, 0x80000000, v139
	s_waitcnt vmcnt(0)
	v_cvt_pk_bf16_f32 v90, v180, v0
	v_cvt_pk_bf16_f32 v91, v181, v39
	v_cvt_pk_bf16_f32 v92, v182, v40
	v_cvt_pk_bf16_f32 v93, v183, v41

; __device__ __forceinline__ void row_pass(const RowPass& rp) {
;     ...
;         if (rp.h) {
;             float ss = 0.f;
; #pragma unroll
;             for (int j = 0; j < 8; ++j) ss += x[j][0] * x[j][0] + x[j][1] * x[j][1] + x[j][2] * x[j][2] + x[j][3] * x[j][3];
;             const float rstd = rsqrtf(wave_sum(ss) * (1.f / D) + EPS);
;             bf16_t* hr = rp.h + (size_t)row * D;
; #pragma unroll
;             for (int j = 0; j < 8; ++j) { const int col = 4 * (lane + 64 * j); const f32x4 gp = *(const f32x4*)(rp.gpre + col); const f32x4 sh = *(const f32x4*)(rp.shv + v * 12288 + col); const f32x4 sc = *(const f32x4*)(rp.scv + v * 12288 + col);
.LBB0_901:
	v_lshlrev_b64 v[250:251], 2, v[76:77]
	v_lshl_add_u64 v[140:141], s[16:17], 0, v[250:251]
	v_lshl_add_u64 v[142:143], s[14:15], 0, v[250:251]
	v_lshl_add_u64 v[144:145], v[140:141], 0, v[0:1]
	v_lshl_add_u64 v[146:147], v[142:143], 0, v[0:1]
	global_load_dwordx4 v[152:155], v[54:55], off offset:1024
	global_load_dwordx4 v[156:159], v[146:147], off offset:1024
	global_load_dwordx4 v[160:163], v[144:145], off offset:1024
	global_load_dwordx4 v[164:167], v[54:55], off offset:2048
	global_load_dwordx4 v[168:171], v[146:147], off offset:2048
	global_load_dwordx4 v[172:175], v[144:145], off offset:2048
	global_load_dwordx4 v[176:179], v[54:55], off offset:3072
	global_load_dwordx4 v[180:183], v[146:147], off offset:3072
	global_load_dwordx4 v[214:217], v[144:145], off offset:3072
	global_load_dwordx4 v[218:221], v[56:57], off
	v_lshl_add_u64 v[246:247], v[142:143], 0, v[66:67]
	global_load_dwordx4 v[222:225], v[246:247], off
	v_lshl_add_u64 v[248:249], v[140:141], 0, v[66:67]
	global_load_dwordx4 v[226:229], v[248:249], off
	global_load_dwordx4 v[230:233], v[58:59], off
	v_lshl_add_u64 v[250:251], v[142:143], 0, v[68:69]
	global_load_dwordx4 v[234:237], v[250:251], off
	v_lshl_add_u64 v[246:247], v[140:141], 0, v[68:69]
	global_load_dwordx4 v[238:241], v[246:247], off
	global_load_dwordx4 v[242:245], v[60:61], off
	v_lshl_add_u64 v[248:249], v[142:143], 0, v[70:71]
	global_load_dwordx4 v[184:187], v[248:249], off
	v_lshl_add_u64 v[250:251], v[140:141], 0, v[70:71]
	global_load_dwordx4 v[136:139], v[250:251], off
	v_mul_f32_e32 v34, v7, v7
	v_mul_f32_e32 v35, v19, v19
	v_fmac_f32_e32 v34, v6, v6
	v_fmac_f32_e32 v35, v18, v18
	v_fmac_f32_e32 v34, v8, v8
	v_fmac_f32_e32 v35, v20, v20
	v_fmac_f32_e32 v34, v9, v9
	v_fmac_f32_e32 v35, v21, v21
	v_add_f32_e32 v34, v34, v35
	v_mul_f32_e32 v35, v23, v23
	v_fmac_f32_e32 v35, v22, v22
	v_fmac_f32_e32 v35, v24, v24
	v_fmac_f32_e32 v35, v25, v25
	v_add_f32_e32 v34, v35, v34
	v_mul_f32_e32 v35, v27, v27
	v_fmac_f32_e32 v35, v26, v26
	v_fmac_f32_e32 v35, v28, v28
	v_fmac_f32_e32 v35, v29, v29
	v_mov_b32_e32 v36, v15
	v_mov_b32_e32 v37, v31
	v_add_f32_e32 v38, v35, v34
	v_mov_b32_e32 v34, v14
	v_mov_b32_e32 v35, v30
	v_pk_mul_f32 v[36:37], v[36:37], v[36:37]
	global_load_dwordx4 v[78:81], v[54:55], off
	v_pk_fma_f32 v[34:35], v[34:35], v[34:35], v[36:37]
	v_mov_b32_e32 v36, v16
	v_mov_b32_e32 v37, v32
	v_pk_fma_f32 v[34:35], v[36:37], v[36:37], v[34:35]
	v_mov_b32_e32 v36, v17
	v_mov_b32_e32 v37, v33
	v_pk_fma_f32 v[34:35], v[36:37], v[36:37], v[34:35]
	v_mov_b32_e32 v36, v3
	v_add_f32_e32 v35, v35, v38
	v_mov_b32_e32 v37, v11
	v_add_f32_e32 v38, v34, v35
	v_mov_b32_e32 v34, v2
	v_mov_b32_e32 v35, v10
	v_pk_mul_f32 v[36:37], v[36:37], v[36:37]
	v_lshl_add_u64 v[42:43], v[42:43], 0, s[44:45]
	v_pk_fma_f32 v[34:35], v[34:35], v[34:35], v[36:37]
	v_mov_b32_e32 v36, v4
	v_mov_b32_e32 v37, v12
	v_pk_fma_f32 v[34:35], v[36:37], v[36:37], v[34:35]
	v_mov_b32_e32 v36, v5
	v_mov_b32_e32 v37, v13
	v_pk_fma_f32 v[34:35], v[36:37], v[36:37], v[34:35]
	v_lshlrev_b64 v[36:37], 2, v[76:77]
	v_add_f32_e32 v35, v35, v38
	v_lshl_add_u64 v[38:39], s[14:15], 0, v[36:37]
	v_lshl_add_u64 v[36:37], s[16:17], 0, v[36:37]
	v_lshl_add_u64 v[74:75], v[36:37], 0, v[0:1]
	v_lshl_add_u64 v[40:41], v[38:39], 0, v[0:1]
	global_load_dwordx4 v[88:91], v[74:75], off
	global_load_dwordx4 v[82:85], v[40:41], off
	v_add_f32_e32 v34, v34, v35
	ds_bpermute_b32 v35, v87, v34
	v_readlane_b32 s0, v255, 9
	v_readlane_b32 s1, v255, 10
	s_waitcnt lgkmcnt(0)
	v_add_f32_e32 v34, v34, v35
	ds_bpermute_b32 v35, v108, v34
	s_waitcnt lgkmcnt(0)
	v_add_f32_e32 v34, v34, v35
	ds_bpermute_b32 v35, v109, v34
	s_waitcnt lgkmcnt(0)
	v_add_f32_e32 v34, v34, v35
	ds_bpermute_b32 v35, v110, v34
	s_waitcnt lgkmcnt(0)
	v_add_f32_e32 v34, v34, v35
	ds_bpermute_b32 v35, v111, v34
	s_waitcnt lgkmcnt(0)
	v_add_f32_e32 v34, v34, v35
	ds_bpermute_b32 v35, v112, v34
	s_waitcnt lgkmcnt(0)
	v_add_f32_e32 v34, v34, v35
	v_fmamk_f32 v34, v34, 0x3a000000, v197
	v_cmp_gt_f32_e32 vcc, s69, v34
	v_mul_f32_e32 v35, 0x4b800000, v34
	s_waitcnt vmcnt(1)
	v_pk_add_f32 v[76:77], v[90:91], 1.0 op_sel_hi:[1,0]
	v_cndmask_b32_e32 v34, v34, v35, vcc
	v_rsq_f32_e32 v34, v34
	s_nop 0
	v_mul_f32_e32 v35, 0x45800000, v34
	v_cndmask_b32_e32 v34, v34, v35, vcc
	v_pk_mul_f32 v[8:9], v[8:9], v[34:35] op_sel_hi:[1,0]
	v_pk_mul_f32 v[6:7], v[6:7], v[34:35] op_sel_hi:[1,0]
	v_pk_mul_f32 v[8:9], v[80:81], v[8:9]
	v_pk_mul_f32 v[6:7], v[78:79], v[6:7]
	v_pk_add_f32 v[78:79], v[88:89], 1.0 op_sel_hi:[1,0]
	s_waitcnt vmcnt(0)
; __device__ __forceinline__ unsigned pk2(float lo, float hi) { return pg8::cvt_pk_bf16(lo, hi); }
; __device__ __forceinline__ void row_pass(const RowPass& rp) {
;     ...
;             const float rstd = rsqrtf(wave_sum(ss) * (1.f / D) + EPS);
;             bf16_t* hr = rp.h + (size_t)row * D;
; #pragma unroll
;             for (int j = 0; j < 8; ++j) { const int col = 4 * (lane + 64 * j); const f32x4 gp = *(const f32x4*)(rp.gpre + col); const f32x4 sh = *(const f32x4*)(rp.shv + v * 12288 + col); const f32x4 sc = *(const f32x4*)(rp.scv + v * 12288 + col);
;                 const f32x4 y = (x[j] * rstd * gp) * (sc + 1.f) + sh; u32x2 w; w.x = pk2(y[0], y[1]); w.y = pk2(y[2], y[3]); *(u32x2*)(hr + col) = w; }
	v_pk_fma_f32 v[8:9], v[76:77], v[8:9], v[84:85]
	v_pk_fma_f32 v[6:7], v[78:79], v[6:7], v[82:83]
	v_pk_mul_f32 v[20:21], v[20:21], v[34:35] op_sel_hi:[1,0]
	v_cvt_pk_bf16_f32 v6, v6, v7
	v_cvt_pk_bf16_f32 v7, v8, v9
	global_store_dwordx2 v[64:65], v[6:7], off
	s_nop 0
	v_pk_mul_f32 v[18:19], v[18:19], v[34:35] op_sel_hi:[1,0]
	v_pk_mul_f32 v[24:25], v[24:25], v[34:35] op_sel_hi:[1,0]
	v_pk_mul_f32 v[22:23], v[22:23], v[34:35] op_sel_hi:[1,0]
	v_pk_mul_f32 v[28:29], v[28:29], v[34:35] op_sel_hi:[1,0]
	v_pk_mul_f32 v[26:27], v[26:27], v[34:35] op_sel_hi:[1,0]
	v_pk_mul_f32 v[16:17], v[16:17], v[34:35] op_sel_hi:[1,0]
	v_pk_mul_f32 v[14:15], v[14:15], v[34:35] op_sel_hi:[1,0]
	v_pk_mul_f32 v[12:13], v[12:13], v[34:35] op_sel_hi:[1,0]
	v_pk_mul_f32 v[10:11], v[10:11], v[34:35] op_sel_hi:[1,0]
	v_pk_mul_f32 v[4:5], v[4:5], v[34:35] op_sel_hi:[1,0]
	v_pk_mul_f32 v[2:3], v[2:3], v[34:35] op_sel_hi:[1,0]
	v_cmp_le_i32_e32 vcc, s36, v42
	s_or_b64 s[18:19], vcc, s[18:19]
	v_pk_mul_f32 v[6:7], v[152:153], v[18:19]
	v_pk_mul_f32 v[8:9], v[154:155], v[20:21]
	v_pk_add_f32 v[18:19], v[162:163], 1.0 op_sel_hi:[1,0]
	v_pk_add_f32 v[20:21], v[160:161], 1.0 op_sel_hi:[1,0]
	v_pk_fma_f32 v[8:9], v[18:19], v[8:9], v[158:159]
	v_pk_fma_f32 v[6:7], v[20:21], v[6:7], v[156:157]
	s_nop 0
	v_cvt_pk_bf16_f32 v6, v6, v7
	v_cvt_pk_bf16_f32 v7, v8, v9
	global_store_dwordx2 v[64:65], v[6:7], off offset:512
	s_nop 0
	v_pk_mul_f32 v[6:7], v[164:165], v[22:23]
	v_pk_mul_f32 v[8:9], v[166:167], v[24:25]
	v_pk_add_f32 v[22:23], v[174:175], 1.0 op_sel_hi:[1,0]
	v_pk_add_f32 v[24:25], v[172:173], 1.0 op_sel_hi:[1,0]
	v_pk_fma_f32 v[8:9], v[22:23], v[8:9], v[170:171]
	v_pk_fma_f32 v[6:7], v[24:25], v[6:7], v[168:169]
	s_nop 0
	v_cvt_pk_bf16_f32 v6, v6, v7
	v_cvt_pk_bf16_f32 v7, v8, v9
	global_store_dwordx2 v[64:65], v[6:7], off offset:1024
	s_nop 0
	v_pk_mul_f32 v[6:7], v[26:27], v[176:177]
	v_pk_mul_f32 v[8:9], v[28:29], v[178:179]
	v_pk_add_f32 v[24:25], v[216:217], 1.0 op_sel_hi:[1,0]
	v_pk_add_f32 v[22:23], v[214:215], 1.0 op_sel_hi:[1,0]
	v_pk_fma_f32 v[8:9], v[8:9], v[24:25], v[182:183]
	v_pk_fma_f32 v[6:7], v[6:7], v[22:23], v[180:181]
	v_lshl_add_u64 v[18:19], v[38:39], 0, v[66:67]
	v_cvt_pk_bf16_f32 v6, v6, v7
	v_cvt_pk_bf16_f32 v7, v8, v9
	global_store_dwordx2 v[64:65], v[6:7], off offset:1536
	v_lshl_add_u64 v[22:23], v[36:37], 0, v[66:67]
	v_pk_mul_f32 v[26:27], v[32:33], v[34:35] op_sel_hi:[1,0]
	v_pk_mul_f32 v[28:29], v[30:31], v[34:35] op_sel_hi:[1,0]
	v_pk_mul_f32 v[6:7], v[28:29], v[218:219]
	v_pk_mul_f32 v[8:9], v[26:27], v[220:221]
	v_pk_add_f32 v[24:25], v[228:229], 1.0 op_sel_hi:[1,0]
	v_pk_add_f32 v[22:23], v[226:227], 1.0 op_sel_hi:[1,0]
	v_pk_fma_f32 v[8:9], v[8:9], v[24:25], v[224:225]
	v_pk_fma_f32 v[6:7], v[6:7], v[22:23], v[222:223]
	v_lshl_add_u64 v[18:19], v[38:39], 0, v[68:69]
	v_cvt_pk_bf16_f32 v6, v6, v7
	v_cvt_pk_bf16_f32 v7, v8, v9
	global_store_dwordx2 v[64:65], v[6:7], off offset:2048
	v_lshl_add_u64 v[22:23], v[36:37], 0, v[68:69]
	v_pk_mul_f32 v[6:7], v[14:15], v[230:231]
	v_pk_mul_f32 v[8:9], v[16:17], v[232:233]
	v_pk_add_f32 v[14:15], v[240:241], 1.0 op_sel_hi:[1,0]
	v_pk_add_f32 v[16:17], v[238:239], 1.0 op_sel_hi:[1,0]
	v_pk_fma_f32 v[8:9], v[8:9], v[14:15], v[236:237]
	v_pk_fma_f32 v[6:7], v[6:7], v[16:17], v[234:235]
	v_lshl_add_u64 v[14:15], v[38:39], 0, v[70:71]
	v_cvt_pk_bf16_f32 v6, v6, v7
	v_cvt_pk_bf16_f32 v7, v8, v9
	global_store_dwordx2 v[64:65], v[6:7], off offset:2560
	v_lshl_add_u64 v[18:19], v[36:37], 0, v[70:71]
	v_pk_mul_f32 v[6:7], v[10:11], v[242:243]
	v_pk_mul_f32 v[8:9], v[12:13], v[244:245]
	v_pk_add_f32 v[10:11], v[138:139], 1.0 op_sel_hi:[1,0]
	v_pk_add_f32 v[12:13], v[136:137], 1.0 op_sel_hi:[1,0]
	v_pk_fma_f32 v[8:9], v[8:9], v[10:11], v[186:187]
	v_pk_fma_f32 v[6:7], v[6:7], v[12:13], v[184:185]
	v_lshl_add_u64 v[10:11], v[38:39], 0, v[72:73]
	v_cvt_pk_bf16_f32 v6, v6, v7
	v_cvt_pk_bf16_f32 v7, v8, v9
	global_store_dwordx2 v[64:65], v[6:7], off offset:3072
	v_lshl_add_u64 v[14:15], v[36:37], 0, v[72:73]
	global_load_dwordx4 v[6:9], v[62:63], off
	s_waitcnt vmcnt(0)
	v_pk_mul_f32 v[2:3], v[2:3], v[6:7]
	global_load_dwordx4 v[10:13], v[10:11], off
	v_pk_mul_f32 v[4:5], v[4:5], v[8:9]
	global_load_dwordx4 v[14:17], v[14:15], off
	s_waitcnt vmcnt(0)
	v_pk_add_f32 v[6:7], v[16:17], 1.0 op_sel_hi:[1,0]
	v_pk_add_f32 v[8:9], v[14:15], 1.0 op_sel_hi:[1,0]
	v_pk_fma_f32 v[4:5], v[4:5], v[6:7], v[12:13]
	v_pk_fma_f32 v[2:3], v[2:3], v[8:9], v[10:11]
	s_nop 0
	v_cvt_pk_bf16_f32 v2, v2, v3
	v_cvt_pk_bf16_f32 v3, v4, v5
	global_store_dwordx2 v[64:65], v[2:3], off offset:3584
	v_lshl_add_u64 v[64:65], v[64:65], 0, s[0:1]
	s_andn2_b64 exec, exec, s[18:19]
	s_cbranch_execz .LBB0_904
; __device__ __forceinline__ void row_pass(const RowPass& rp) {
;     ...
;         const int v = (row < MLAT) ? (row >> 12) : 2;
;         const float* xs = (row < MLAT) ? rp.src_lat + (size_t)row * D : rp.src_ctx + (size_t)(row - MLAT) * D;
;         f32x4 x[8];
; #pragma unroll
;         for (int j = 0; j < 8; ++j) x[j] = *(const f32x4*)(xs + 4 * (lane + 64 * j));
;         if (rp.o) {
;             const bf16_t* orow = rp.o + (size_t)row * D; f32x4 ov[8]; float ss = 0.f;
; #pragma unroll
;             for (int j = 0; j < 8; ++j) { const u32x2 w2 = *(const u32x2*)(orow + 4 * (lane + 64 * j));
;                 ov[j] = (f32x4){__uint_as_float(w2.x << 16), __uint_as_float(w2.x & 0xffff0000u), __uint_as_float(w2.y << 16), __uint_as_float(w2.y & 0xffff0000u)};
;                 ss += ov[j][0] * ov[j][0] + ov[j][1] * ov[j][1] + ov[j][2] * ov[j][2] + ov[j][3] * ov[j][3]; }
;             const float rstd = rsqrtf(wave_sum(ss) * (1.f / D) + EPS);
; #pragma unroll
;             for (int j = 0; j < 8; ++j) { const int col = 4 * (lane + 64 * j); const f32x4 gp = *(const f32x4*)(rp.gpost + col); const f32x4 gt = *(const f32x4*)(rp.gatev + v * 12288 + col);
;                 x[j] = x[j] + gt * (ov[j] * rstd * gp); }
.LBB0_902:
	v_min_i32_e32 v2, 0x2000, v42
	v_cmp_gt_i32_e64 s[0:1], s70, v42
	v_ashrrev_i32_e32 v106, 12, v2
	v_add_u32_e32 v2, 0xffffe000, v42
	v_mov_b32_e32 v4, s9
	v_mov_b32_e32 v5, s4
	v_cndmask_b32_e64 v3, 0, v43, s[0:1]
	v_cndmask_b32_e64 v2, v2, v42, s[0:1]
	v_cndmask_b32_e64 v5, v4, v5, s[0:1]
	v_mov_b32_e32 v4, s20
	v_mov_b32_e32 v6, s5
	v_cndmask_b32_e64 v4, v4, v6, s[0:1]
	v_lshlrev_b64 v[74:75], 13, v[2:3]
	s_mov_b32 s21, 0xd400000
	v_lshl_add_u64 v[2:3], v[4:5], 0, v[74:75]
	v_add_co_u32_e32 v34, vcc, s21, v64
	v_lshl_add_u64 v[4:5], v[2:3], 0, v[0:1]
	s_nop 0
	v_addc_co_u32_e32 v35, vcc, 0, v65, vcc
	global_load_dwordx4 v[6:9], v[4:5], off
	global_load_dwordx4 v[18:21], v[4:5], off offset:1024
	global_load_dwordx4 v[22:25], v[4:5], off offset:2048
	global_load_dwordx4 v[26:29], v[4:5], off offset:3072
	global_load_dwordx2 v[36:37], v[34:35], off
	v_mov_b32_e32 v67, v1
	v_lshl_add_u64 v[4:5], v[2:3], 0, v[66:67]
	v_mov_b32_e32 v69, v1
	global_load_dwordx4 v[30:33], v[4:5], off
	v_lshl_add_u64 v[4:5], v[2:3], 0, v[68:69]
	v_mov_b32_e32 v71, v1
	v_mov_b32_e32 v73, v1
	global_load_dwordx4 v[14:17], v[4:5], off
	v_lshl_add_u64 v[4:5], v[2:3], 0, v[70:71]
	v_lshl_add_u64 v[2:3], v[2:3], 0, v[72:73]
	global_load_dwordx4 v[10:13], v[4:5], off
	v_readlane_b32 s22, v254, 16
	global_load_dwordx4 v[2:5], v[2:3], off
	global_load_dwordx2 v[122:123], v[34:35], off offset:512
	global_load_dwordx2 v[124:125], v[34:35], off offset:1024
	global_load_dwordx2 v[126:127], v[34:35], off offset:1536
	global_load_dwordx2 v[128:129], v[34:35], off offset:2048
	global_load_dwordx2 v[130:131], v[34:35], off offset:2560
	global_load_dwordx2 v[132:133], v[34:35], off offset:3072
	global_load_dwordx2 v[134:135], v[34:35], off offset:3584
	v_mul_i32_i24_e32 v140, 0x3000, v106
	v_ashrrev_i32_e32 v141, 31, v140
	v_lshl_add_u64 v[140:141], v[140:141], 2, s[10:11]
	v_lshl_add_u64 v[142:143], v[140:141], 0, v[0:1]
	v_lshl_add_u64 v[144:145], v[140:141], 0, v[66:67]
	v_lshl_add_u64 v[146:147], v[140:141], 0, v[68:69]
	v_lshl_add_u64 v[246:247], v[140:141], 0, v[70:71]
	v_lshl_add_u64 v[248:249], v[140:141], 0, v[72:73]
	global_load_dwordx4 v[152:155], v[44:45], off
	global_load_dwordx4 v[214:217], v[142:143], off
	global_load_dwordx4 v[156:159], v[44:45], off offset:1024
	global_load_dwordx4 v[218:221], v[142:143], off offset:1024
	global_load_dwordx4 v[160:163], v[44:45], off offset:2048
	global_load_dwordx4 v[222:225], v[142:143], off offset:2048
	global_load_dwordx4 v[164:167], v[44:45], off offset:3072
	global_load_dwordx4 v[226:229], v[142:143], off offset:3072
	global_load_dwordx4 v[168:171], v[46:47], off
	global_load_dwordx4 v[230:233], v[144:145], off
	global_load_dwordx4 v[172:175], v[48:49], off
	global_load_dwordx4 v[234:237], v[146:147], off
	global_load_dwordx4 v[176:179], v[50:51], off
	global_load_dwordx4 v[238:241], v[246:247], off
	global_load_dwordx4 v[180:183], v[52:53], off
	global_load_dwordx4 v[242:245], v[248:249], off
	v_readlane_b32 s23, v254, 17
	s_waitcnt vmcnt(27)
	v_lshlrev_b32_e32 v102, 16, v36
	v_and_b32_e32 v103, 0xffff0000, v36
	v_lshlrev_b32_e32 v104, 16, v37
	v_and_b32_e32 v105, 0xffff0000, v37
	v_mul_f32_e32 v38, v103, v103
	v_fmac_f32_e32 v38, v102, v102
	v_fmac_f32_e32 v38, v104, v104
	v_fmac_f32_e32 v38, v105, v105
	s_waitcnt vmcnt(22)
	v_and_b32_e32 v99, 0xffff0000, v122
	v_lshlrev_b32_e32 v98, 16, v122
	v_mul_f32_e32 v36, v99, v99
	v_lshlrev_b32_e32 v100, 16, v123
	v_fmac_f32_e32 v36, v98, v98
	v_and_b32_e32 v101, 0xffff0000, v123
	v_fmac_f32_e32 v36, v100, v100
	v_fmac_f32_e32 v36, v101, v101
	v_add_f32_e32 v38, v38, v36
	s_waitcnt vmcnt(21)
	v_and_b32_e32 v95, 0xffff0000, v124
	v_lshlrev_b32_e32 v94, 16, v124
	v_mul_f32_e32 v36, v95, v95
	v_lshlrev_b32_e32 v96, 16, v125
	v_fmac_f32_e32 v36, v94, v94
	v_and_b32_e32 v97, 0xffff0000, v125
	v_fmac_f32_e32 v36, v96, v96
	v_fmac_f32_e32 v36, v97, v97
	v_add_f32_e32 v38, v38, v36
	s_waitcnt vmcnt(19)
	v_lshlrev_b32_e32 v40, 16, v129
	v_and_b32_e32 v91, 0xffff0000, v126
	v_lshlrev_b32_e32 v90, 16, v126
	v_mul_f32_e32 v36, v91, v91
	v_lshlrev_b32_e32 v92, 16, v127
	v_fmac_f32_e32 v36, v90, v90
	v_and_b32_e32 v93, 0xffff0000, v127
	v_fmac_f32_e32 v36, v92, v92
	v_fmac_f32_e32 v36, v93, v93
	v_add_f32_e32 v80, v38, v36
	s_waitcnt vmcnt(18)
	v_and_b32_e32 v39, 0xffff0000, v130
	v_and_b32_e32 v38, 0xffff0000, v128
	v_lshlrev_b32_e32 v37, 16, v130
	v_lshlrev_b32_e32 v36, 16, v128
	v_and_b32_e32 v88, 0xffff0000, v129
	v_pk_mul_f32 v[76:77], v[38:39], v[38:39]
	v_lshlrev_b32_e32 v41, 16, v131
	v_pk_fma_f32 v[76:77], v[36:37], v[36:37], v[76:77]
	v_and_b32_e32 v89, 0xffff0000, v131
	v_pk_fma_f32 v[76:77], v[40:41], v[40:41], v[76:77]
	s_nop 0
	v_pk_fma_f32 v[76:77], v[88:89], v[88:89], v[76:77]
	s_nop 0
	v_add_f32_e32 v76, v80, v76
	v_add_f32_e32 v86, v76, v77
	s_nop 0
	s_waitcnt vmcnt(17)
	v_and_b32_e32 v78, 0xffff0000, v132
	s_waitcnt vmcnt(16)
	v_and_b32_e32 v79, 0xffff0000, v134
	v_lshlrev_b32_e32 v81, 16, v134
	v_lshlrev_b32_e32 v80, 16, v132
	v_lshlrev_b32_e32 v85, 16, v135
	v_and_b32_e32 v83, 0xffff0000, v135
	v_pk_mul_f32 v[34:35], v[78:79], v[78:79]
	v_lshlrev_b32_e32 v84, 16, v133
	v_pk_fma_f32 v[34:35], v[80:81], v[80:81], v[34:35]
	v_and_b32_e32 v82, 0xffff0000, v133
	v_pk_fma_f32 v[34:35], v[84:85], v[84:85], v[34:35]
	v_mul_i32_i24_e32 v76, 0x3000, v106
	v_pk_fma_f32 v[34:35], v[82:83], v[82:83], v[34:35]
	v_ashrrev_i32_e32 v77, 31, v76
	v_add_f32_e32 v34, v86, v34
	v_add_f32_e32 v34, v34, v35
	ds_bpermute_b32 v35, v87, v34
	s_waitcnt lgkmcnt(0)
; __device__ __forceinline__ void row_pass(const RowPass& rp) {
;     ...
;             const float rstd = rsqrtf(wave_sum(ss) * (1.f / D) + EPS);
; #pragma unroll
;             for (int j = 0; j < 8; ++j) { const int col = 4 * (lane + 64 * j); const f32x4 gp = *(const f32x4*)(rp.gpost + col); const f32x4 gt = *(const f32x4*)(rp.gatev + v * 12288 + col);
;                 x[j] = x[j] + gt * (ov[j] * rstd * gp); }
;         }
;         if (rp.dst_lat) { float* xd = (row < MLAT) ? rp.dst_lat + (size_t)row * D : rp.dst_ctx + (size_t)(row - MLAT) * D;
; #pragma unroll
;             for (int j = 0; j < 8; ++j) *(f32x4*)(xd + 4 * (lane + 64 * j)) = x[j]; }
	v_add_f32_e32 v34, v34, v35
	ds_bpermute_b32 v35, v108, v34
	s_waitcnt lgkmcnt(0)
	v_add_f32_e32 v34, v34, v35
	ds_bpermute_b32 v35, v109, v34
	s_waitcnt lgkmcnt(0)
	v_add_f32_e32 v34, v34, v35
	ds_bpermute_b32 v35, v110, v34
	s_waitcnt lgkmcnt(0)
	v_add_f32_e32 v34, v34, v35
	ds_bpermute_b32 v35, v111, v34
	s_waitcnt lgkmcnt(0)
	v_add_f32_e32 v34, v34, v35
	ds_bpermute_b32 v35, v112, v34
	s_waitcnt lgkmcnt(0)
	v_add_f32_e32 v34, v34, v35
	v_fmamk_f32 v34, v34, 0x3a000000, v197
	v_cmp_gt_f32_e32 vcc, s69, v34
	v_mul_f32_e32 v35, 0x4b800000, v34
	s_nop 0
	v_cndmask_b32_e32 v34, v34, v35, vcc
	v_rsq_f32_e32 v34, v34
	s_nop 0
	v_mul_f32_e32 v35, 0x45800000, v34
	v_cndmask_b32_e32 v86, v34, v35, vcc
	v_lshl_add_u64 v[34:35], v[76:77], 2, s[10:11]
	v_lshl_add_u64 v[106:107], v[34:35], 0, v[0:1]
	v_pk_mul_f32 v[104:105], v[104:105], v[86:87] op_sel_hi:[1,0]
	v_pk_mul_f32 v[102:103], v[102:103], v[86:87] op_sel_hi:[1,0]
	v_pk_mul_f32 v[100:101], v[100:101], v[86:87] op_sel_hi:[1,0]
	v_pk_mul_f32 v[98:99], v[98:99], v[86:87] op_sel_hi:[1,0]
	v_pk_mul_f32 v[96:97], v[96:97], v[86:87] op_sel_hi:[1,0]
	v_pk_mul_f32 v[94:95], v[94:95], v[86:87] op_sel_hi:[1,0]
	v_pk_mul_f32 v[92:93], v[92:93], v[86:87] op_sel_hi:[1,0]
	v_pk_mul_f32 v[90:91], v[90:91], v[86:87] op_sel_hi:[1,0]
	s_andn2_b64 vcc, exec, s[22:23]
	s_waitcnt vmcnt(15)
	v_pk_mul_f32 v[102:103], v[152:153], v[102:103]
	v_pk_mul_f32 v[104:105], v[154:155], v[104:105]
	s_waitcnt vmcnt(14)
	v_pk_fma_f32 v[6:7], v[214:215], v[102:103], v[6:7]
	v_pk_fma_f32 v[8:9], v[216:217], v[104:105], v[8:9]
	s_waitcnt vmcnt(13)
	v_pk_mul_f32 v[98:99], v[156:157], v[98:99]
	v_pk_mul_f32 v[100:101], v[158:159], v[100:101]
	s_waitcnt vmcnt(12)
	v_pk_fma_f32 v[18:19], v[218:219], v[98:99], v[18:19]
	v_pk_fma_f32 v[20:21], v[220:221], v[100:101], v[20:21]
	s_waitcnt vmcnt(11)
	v_pk_mul_f32 v[94:95], v[160:161], v[94:95]
	v_pk_mul_f32 v[96:97], v[162:163], v[96:97]
	s_waitcnt vmcnt(10)
	v_pk_fma_f32 v[22:23], v[222:223], v[94:95], v[22:23]
	v_pk_fma_f32 v[24:25], v[224:225], v[96:97], v[24:25]
	s_waitcnt vmcnt(9)
	v_pk_mul_f32 v[90:91], v[164:165], v[90:91]
	v_pk_mul_f32 v[92:93], v[166:167], v[92:93]
	s_waitcnt vmcnt(8)
	v_pk_fma_f32 v[26:27], v[226:227], v[90:91], v[26:27]
	v_pk_fma_f32 v[28:29], v[228:229], v[92:93], v[28:29]
	v_lshl_add_u64 v[94:95], v[34:35], 0, v[66:67]
	v_mov_b32_e32 v98, v40
	v_mov_b32_e32 v99, v88
	v_mov_b32_e32 v100, v36
	v_mov_b32_e32 v101, v38
	v_pk_mul_f32 v[98:99], v[98:99], v[86:87] op_sel_hi:[1,0]
	v_pk_mul_f32 v[100:101], v[100:101], v[86:87] op_sel_hi:[1,0]
	v_mov_b32_e32 v88, v41
	v_mov_b32_e32 v38, v37
	v_pk_mul_f32 v[40:41], v[88:89], v[86:87] op_sel_hi:[1,0]
	v_pk_mul_f32 v[36:37], v[38:39], v[86:87] op_sel_hi:[1,0]
	s_waitcnt vmcnt(7)
	v_pk_mul_f32 v[90:91], v[168:169], v[100:101]
	v_pk_mul_f32 v[92:93], v[170:171], v[98:99]
	s_waitcnt vmcnt(6)
	v_pk_fma_f32 v[30:31], v[230:231], v[90:91], v[30:31]
	v_pk_fma_f32 v[32:33], v[232:233], v[92:93], v[32:33]
	v_lshl_add_u64 v[94:95], v[34:35], 0, v[68:69]
	s_waitcnt vmcnt(5)
	v_pk_mul_f32 v[36:37], v[172:173], v[36:37]
	v_pk_mul_f32 v[38:39], v[174:175], v[40:41]
	s_waitcnt vmcnt(4)
	v_pk_fma_f32 v[14:15], v[234:235], v[36:37], v[14:15]
	v_pk_fma_f32 v[16:17], v[236:237], v[38:39], v[16:17]
	v_lshl_add_u64 v[40:41], v[34:35], 0, v[70:71]
	v_mov_b32_e32 v40, v84
	v_mov_b32_e32 v41, v82
	v_pk_mul_f32 v[40:41], v[40:41], v[86:87] op_sel_hi:[1,0]
	v_mov_b32_e32 v92, v80
	v_mov_b32_e32 v93, v78
	v_pk_mul_f32 v[92:93], v[92:93], v[86:87] op_sel_hi:[1,0]
	v_lshl_add_u64 v[34:35], v[34:35], 0, v[72:73]
	v_mov_b32_e32 v82, v85
	v_mov_b32_e32 v78, v81
	v_pk_mul_f32 v[82:83], v[82:83], v[86:87] op_sel_hi:[1,0]
	v_pk_mul_f32 v[78:79], v[78:79], v[86:87] op_sel_hi:[1,0]
	s_waitcnt vmcnt(3)
	v_pk_mul_f32 v[38:39], v[178:179], v[40:41]
	v_pk_mul_f32 v[36:37], v[176:177], v[92:93]
	s_waitcnt vmcnt(2)
	v_pk_fma_f32 v[12:13], v[240:241], v[38:39], v[12:13]
	v_pk_fma_f32 v[10:11], v[238:239], v[36:37], v[10:11]
	s_waitcnt vmcnt(1)
	v_pk_mul_f32 v[38:39], v[180:181], v[78:79]
	v_pk_mul_f32 v[40:41], v[182:183], v[82:83]
	s_waitcnt vmcnt(0)
	v_pk_fma_f32 v[2:3], v[242:243], v[38:39], v[2:3]
	v_pk_fma_f32 v[4:5], v[244:245], v[40:41], v[4:5]
	s_cbranch_vccnz .LBB0_901
	v_readlane_b32 s21, v252, 57
	v_mov_b32_e32 v35, s85
	v_mov_b32_e32 v36, s84
	v_mov_b32_e32 v34, s21
	v_readlane_b32 s21, v252, 56
	v_cndmask_b32_e64 v35, v34, v35, s[0:1]
	s_nop 0
	v_mov_b32_e32 v34, s21
	v_cndmask_b32_e64 v34, v34, v36, s[0:1]
	v_lshl_add_u64 v[34:35], v[34:35], 0, v[74:75]
	v_lshl_add_u64 v[36:37], v[34:35], 0, v[0:1]
	global_store_dwordx4 v[36:37], v[6:9], off
	global_store_dwordx4 v[36:37], v[18:21], off offset:1024
	global_store_dwordx4 v[36:37], v[22:25], off offset:2048
	global_store_dwordx4 v[36:37], v[26:29], off offset:3072
	v_lshl_add_u64 v[36:37], v[34:35], 0, v[66:67]
	global_store_dwordx4 v[36:37], v[30:33], off
	v_lshl_add_u64 v[36:37], v[34:35], 0, v[68:69]
	global_store_dwordx4 v[36:37], v[14:17], off
	v_lshl_add_u64 v[36:37], v[34:35], 0, v[70:71]
	v_lshl_add_u64 v[34:35], v[34:35], 0, v[72:73]
	global_store_dwordx4 v[36:37], v[10:13], off
	global_store_dwordx4 v[34:35], v[2:5], off
	s_branch .LBB0_901

; __device__ __forceinline__ void row_pass(const RowPass& rp) {
;     ...
;         const int v = (row < MLAT) ? (row >> 12) : 2;
;         const float* xs = (row < MLAT) ? rp.src_lat + (size_t)row * D : rp.src_ctx + (size_t)(row - MLAT) * D;
;         f32x4 x[8];
; #pragma unroll
;         for (int j = 0; j < 8; ++j) x[j] = *(const f32x4*)(xs + 4 * (lane + 64 * j));
;         if (rp.o) {
;             const bf16_t* orow = rp.o + (size_t)row * D; f32x4 ov[8]; float ss = 0.f;
; #pragma unroll
;             for (int j = 0; j < 8; ++j) { const u32x2 w2 = *(const u32x2*)(orow + 4 * (lane + 64 * j));
;                 ov[j] = (f32x4){__uint_as_float(w2.x << 16), __uint_as_float(w2.x & 0xffff0000u), __uint_as_float(w2.y << 16), __uint_as_float(w2.y & 0xffff0000u)};
;                 ss += ov[j][0] * ov[j][0] + ov[j][1] * ov[j][1] + ov[j][2] * ov[j][2] + ov[j][3] * ov[j][3]; }
;             const float rstd = rsqrtf(wave_sum(ss) * (1.f / D) + EPS);
; #pragma unroll
;             for (int j = 0; j < 8; ++j) { const int col = 4 * (lane + 64 * j); const f32x4 gp = *(const f32x4*)(rp.gpost + col); const f32x4 gt = *(const f32x4*)(rp.gatev + v * 12288 + col);
;                 x[j] = x[j] + gt * (ov[j] * rstd * gp); }
.LBB0_1133:
	v_min_i32_e32 v0, 0x2000, v42
	v_cmp_gt_i32_e32 vcc, s70, v42
	v_ashrrev_i32_e32 v98, 12, v0
	v_add_u32_e32 v0, 0xffffe000, v42
	v_readlane_b32 s16, v252, 57
	v_cndmask_b32_e32 v2, v0, v42, vcc
	v_mov_b32_e32 v4, s85
	v_mov_b32_e32 v0, s16
	v_readlane_b32 s16, v252, 56
	v_cndmask_b32_e32 v3, 0, v43, vcc
	v_cndmask_b32_e32 v5, v0, v4, vcc
	v_mov_b32_e32 v0, s16
	v_mov_b32_e32 v4, s84
	v_cndmask_b32_e32 v4, v0, v4, vcc
	v_lshlrev_b64 v[2:3], 13, v[2:3]
	v_lshl_add_u64 v[34:35], v[78:79], 0, v[74:75]
	s_mov_b32 s16, 0x23a00000
	v_lshl_add_u64 v[2:3], v[4:5], 0, v[2:3]
	v_lshlrev_b32_e32 v0, 2, v44
	v_add_co_u32_e32 v34, vcc, s16, v34
	v_lshl_add_u64 v[88:89], v[2:3], 0, v[0:1]
	s_nop 0
	v_addc_co_u32_e32 v35, vcc, 0, v35, vcc
	global_load_dwordx4 v[6:9], v[88:89], off
	global_load_dwordx4 v[18:21], v[88:89], off offset:1024
	global_load_dwordx4 v[26:29], v[88:89], off offset:2048
	global_load_dwordx4 v[30:33], v[88:89], off offset:3072
	global_load_dwordx2 v[36:37], v[34:35], off
	v_lshlrev_b32_e32 v86, 2, v46
	v_mov_b32_e32 v87, v1
	v_lshlrev_b32_e32 v84, 2, v48
	v_mov_b32_e32 v85, v1
	v_lshlrev_b32_e32 v82, 2, v50
	v_mov_b32_e32 v83, v1
	v_lshlrev_b32_e32 v80, 2, v52
	v_mov_b32_e32 v81, v1
	v_lshl_add_u64 v[90:91], v[2:3], 0, v[86:87]
	v_lshl_add_u64 v[92:93], v[2:3], 0, v[84:85]
	v_lshl_add_u64 v[94:95], v[2:3], 0, v[82:83]
	v_lshl_add_u64 v[96:97], v[2:3], 0, v[80:81]
	global_load_dwordx4 v[22:25], v[90:91], off
	global_load_dwordx4 v[14:17], v[92:93], off
	global_load_dwordx4 v[10:13], v[94:95], off
	global_load_dwordx4 v[2:5], v[96:97], off
	global_load_dwordx2 v[138:139], v[34:35], off offset:512
	global_load_dwordx2 v[140:141], v[34:35], off offset:1024
	global_load_dwordx2 v[142:143], v[34:35], off offset:1536
	global_load_dwordx2 v[100:101], v[34:35], off offset:2048
	global_load_dwordx2 v[102:103], v[34:35], off offset:2560
	global_load_dwordx2 v[128:129], v[34:35], off offset:3072
	s_nop 0
	global_load_dwordx2 v[34:35], v[34:35], off offset:3584
	v_mul_i32_i24_e32 v144, 0x3000, v98
	v_ashrrev_i32_e32 v145, 31, v144
	v_lshl_add_u64 v[144:145], v[144:145], 2, s[8:9]
	v_lshl_add_u64 v[146:147], v[144:145], 0, v[0:1]
	global_load_dwordx4 v[152:155], v[54:55], off
	global_load_dwordx4 v[214:217], v[146:147], off
	global_load_dwordx4 v[156:159], v[54:55], off offset:1024
	global_load_dwordx4 v[218:221], v[146:147], off offset:1024
	global_load_dwordx4 v[160:163], v[54:55], off offset:2048
	global_load_dwordx4 v[222:225], v[146:147], off offset:2048
	global_load_dwordx4 v[164:167], v[54:55], off offset:3072
	global_load_dwordx4 v[226:229], v[146:147], off offset:3072
	global_load_dwordx4 v[168:171], v[56:57], off
	v_lshl_add_u64 v[246:247], v[144:145], 0, v[86:87]
	global_load_dwordx4 v[230:233], v[246:247], off
	global_load_dwordx4 v[172:175], v[58:59], off
	v_lshl_add_u64 v[248:249], v[144:145], 0, v[84:85]
	global_load_dwordx4 v[234:237], v[248:249], off
	global_load_dwordx4 v[176:179], v[60:61], off
	v_lshl_add_u64 v[250:251], v[144:145], 0, v[82:83]
	global_load_dwordx4 v[238:241], v[250:251], off
	global_load_dwordx4 v[180:183], v[62:63], off
	v_lshl_add_u64 v[246:247], v[144:145], 0, v[80:81]
	global_load_dwordx4 v[242:245], v[246:247], off
	v_mul_i32_i24_e32 v98, 0x3000, v98
	v_readlane_b32 s16, v254, 16
	v_readlane_b32 s17, v254, 17
	s_waitcnt vmcnt(27)
	v_lshlrev_b32_e32 v124, 16, v36
	v_and_b32_e32 v125, 0xffff0000, v36
	v_lshlrev_b32_e32 v126, 16, v37
	v_and_b32_e32 v127, 0xffff0000, v37
	v_mul_f32_e32 v38, v125, v125
	v_fmac_f32_e32 v38, v124, v124
	v_fmac_f32_e32 v38, v126, v126
	v_fmac_f32_e32 v38, v127, v127
	s_waitcnt vmcnt(22)
	v_and_b32_e32 v121, 0xffff0000, v138
	v_lshlrev_b32_e32 v120, 16, v138
	v_mul_f32_e32 v36, v121, v121
	v_lshlrev_b32_e32 v122, 16, v139
	v_fmac_f32_e32 v36, v120, v120
	v_and_b32_e32 v123, 0xffff0000, v139
	v_fmac_f32_e32 v36, v122, v122
	v_fmac_f32_e32 v36, v123, v123
	v_add_f32_e32 v38, v38, v36
	s_waitcnt vmcnt(21)
	v_and_b32_e32 v117, 0xffff0000, v140
	v_lshlrev_b32_e32 v116, 16, v140
	v_mul_f32_e32 v36, v117, v117
	v_lshlrev_b32_e32 v118, 16, v141
	v_fmac_f32_e32 v36, v116, v116
	v_and_b32_e32 v119, 0xffff0000, v141
	v_fmac_f32_e32 v36, v118, v118
	v_fmac_f32_e32 v36, v119, v119
	v_add_f32_e32 v38, v38, v36
	s_waitcnt vmcnt(19)
	v_lshlrev_b32_e32 v40, 16, v101
	v_and_b32_e32 v113, 0xffff0000, v142
	v_lshlrev_b32_e32 v112, 16, v142
	v_mul_f32_e32 v36, v113, v113
	v_lshlrev_b32_e32 v114, 16, v143
	v_fmac_f32_e32 v36, v112, v112
	v_and_b32_e32 v115, 0xffff0000, v143
	v_fmac_f32_e32 v36, v114, v114
	v_fmac_f32_e32 v36, v115, v115
	v_add_f32_e32 v99, v38, v36
	s_waitcnt vmcnt(18)
	v_and_b32_e32 v39, 0xffff0000, v102
	v_and_b32_e32 v38, 0xffff0000, v100
	v_lshlrev_b32_e32 v37, 16, v102
	v_lshlrev_b32_e32 v36, 16, v100
	v_and_b32_e32 v110, 0xffff0000, v101
	v_pk_mul_f32 v[100:101], v[38:39], v[38:39]
	v_lshlrev_b32_e32 v41, 16, v103
	v_pk_fma_f32 v[100:101], v[36:37], v[36:37], v[100:101]
	v_and_b32_e32 v111, 0xffff0000, v103
	v_pk_fma_f32 v[100:101], v[40:41], v[40:41], v[100:101]
	s_waitcnt vmcnt(16)
	v_lshlrev_b32_e32 v103, 16, v34
	v_pk_fma_f32 v[100:101], v[110:111], v[110:111], v[100:101]
	v_lshlrev_b32_e32 v102, 16, v128
	v_add_f32_e32 v99, v99, v100
	v_add_f32_e32 v99, v99, v101
	v_and_b32_e32 v101, 0xffff0000, v34
	v_and_b32_e32 v100, 0xffff0000, v128
	v_lshlrev_b32_e32 v107, 16, v35
	v_and_b32_e32 v105, 0xffff0000, v35
	v_pk_mul_f32 v[34:35], v[100:101], v[100:101]
	v_lshlrev_b32_e32 v106, 16, v129
	v_pk_fma_f32 v[34:35], v[102:103], v[102:103], v[34:35]
	v_and_b32_e32 v104, 0xffff0000, v129
	v_pk_fma_f32 v[34:35], v[106:107], v[106:107], v[34:35]
	v_pk_fma_f32 v[34:35], v[104:105], v[104:105], v[34:35]
	s_nop 0
	v_add_f32_e32 v34, v99, v34
	v_add_f32_e32 v34, v34, v35
	ds_bpermute_b32 v35, v45, v34
	v_ashrrev_i32_e32 v99, 31, v98
	s_waitcnt lgkmcnt(0)
; __device__ __forceinline__ void row_pass(const RowPass& rp) {
;     ...
;             const float rstd = rsqrtf(wave_sum(ss) * (1.f / D) + EPS);
; #pragma unroll
;             for (int j = 0; j < 8; ++j) { const int col = 4 * (lane + 64 * j); const f32x4 gp = *(const f32x4*)(rp.gpost + col); const f32x4 gt = *(const f32x4*)(rp.gatev + v * 12288 + col);
;                 x[j] = x[j] + gt * (ov[j] * rstd * gp); }
;         }
;         if (rp.dst_lat) { float* xd = (row < MLAT) ? rp.dst_lat + (size_t)row * D : rp.dst_ctx + (size_t)(row - MLAT) * D;
; #pragma unroll
;             for (int j = 0; j < 8; ++j) *(f32x4*)(xd + 4 * (lane + 64 * j)) = x[j]; }
	v_add_f32_e32 v34, v34, v35
	ds_bpermute_b32 v35, v47, v34
	s_waitcnt lgkmcnt(0)
	v_add_f32_e32 v34, v34, v35
	ds_bpermute_b32 v35, v49, v34
	s_waitcnt lgkmcnt(0)
	v_add_f32_e32 v34, v34, v35
	ds_bpermute_b32 v35, v51, v34
	s_waitcnt lgkmcnt(0)
	v_add_f32_e32 v34, v34, v35
	ds_bpermute_b32 v35, v53, v34
	s_waitcnt lgkmcnt(0)
	v_add_f32_e32 v34, v34, v35
	ds_bpermute_b32 v35, v109, v34
	s_waitcnt lgkmcnt(0)
	v_add_f32_e32 v34, v34, v35
	v_fmamk_f32 v34, v34, 0x3a000000, v197
	v_cmp_gt_f32_e32 vcc, s69, v34
	v_mul_f32_e32 v35, 0x4b800000, v34
	s_nop 0
	v_cndmask_b32_e32 v34, v34, v35, vcc
	v_rsq_f32_e32 v34, v34
	s_nop 0
	v_mul_f32_e32 v35, 0x45800000, v34
	v_cndmask_b32_e32 v108, v34, v35, vcc
	v_lshl_add_u64 v[34:35], v[98:99], 2, s[8:9]
	v_lshl_add_u64 v[128:129], v[34:35], 0, v[0:1]
	v_pk_mul_f32 v[126:127], v[126:127], v[108:109] op_sel_hi:[1,0]
	v_pk_mul_f32 v[124:125], v[124:125], v[108:109] op_sel_hi:[1,0]
	v_pk_mul_f32 v[122:123], v[122:123], v[108:109] op_sel_hi:[1,0]
	v_pk_mul_f32 v[120:121], v[120:121], v[108:109] op_sel_hi:[1,0]
	v_pk_mul_f32 v[118:119], v[118:119], v[108:109] op_sel_hi:[1,0]
	v_pk_mul_f32 v[116:117], v[116:117], v[108:109] op_sel_hi:[1,0]
	v_pk_mul_f32 v[114:115], v[114:115], v[108:109] op_sel_hi:[1,0]
	v_pk_mul_f32 v[112:113], v[112:113], v[108:109] op_sel_hi:[1,0]
	s_andn2_b64 vcc, exec, s[16:17]
	s_waitcnt vmcnt(15)
	v_pk_mul_f32 v[124:125], v[152:153], v[124:125]
	v_pk_mul_f32 v[126:127], v[154:155], v[126:127]
	s_waitcnt vmcnt(14)
	v_pk_fma_f32 v[6:7], v[214:215], v[124:125], v[6:7]
	v_pk_fma_f32 v[8:9], v[216:217], v[126:127], v[8:9]
	s_waitcnt vmcnt(13)
	v_pk_mul_f32 v[120:121], v[156:157], v[120:121]
	v_pk_mul_f32 v[122:123], v[158:159], v[122:123]
	s_waitcnt vmcnt(12)
	v_pk_fma_f32 v[18:19], v[218:219], v[120:121], v[18:19]
	v_pk_fma_f32 v[20:21], v[220:221], v[122:123], v[20:21]
	s_waitcnt vmcnt(11)
	v_pk_mul_f32 v[116:117], v[160:161], v[116:117]
	v_pk_mul_f32 v[118:119], v[162:163], v[118:119]
	s_waitcnt vmcnt(10)
	v_pk_fma_f32 v[26:27], v[222:223], v[116:117], v[26:27]
	v_pk_fma_f32 v[28:29], v[224:225], v[118:119], v[28:29]
	s_waitcnt vmcnt(9)
	v_pk_mul_f32 v[112:113], v[164:165], v[112:113]
	v_pk_mul_f32 v[114:115], v[166:167], v[114:115]
	s_waitcnt vmcnt(8)
	v_pk_fma_f32 v[30:31], v[226:227], v[112:113], v[30:31]
	v_pk_fma_f32 v[32:33], v[228:229], v[114:115], v[32:33]
	v_lshl_add_u64 v[116:117], v[34:35], 0, v[86:87]
	v_mov_b32_e32 v120, v40
	v_mov_b32_e32 v121, v110
	v_mov_b32_e32 v122, v36
	v_mov_b32_e32 v123, v38
	v_pk_mul_f32 v[120:121], v[120:121], v[108:109] op_sel_hi:[1,0]
	v_pk_mul_f32 v[122:123], v[122:123], v[108:109] op_sel_hi:[1,0]
	v_mov_b32_e32 v110, v41
	v_mov_b32_e32 v38, v37
	v_pk_mul_f32 v[40:41], v[110:111], v[108:109] op_sel_hi:[1,0]
	v_pk_mul_f32 v[36:37], v[38:39], v[108:109] op_sel_hi:[1,0]
	s_waitcnt vmcnt(7)
	v_pk_mul_f32 v[112:113], v[168:169], v[122:123]
	v_pk_mul_f32 v[114:115], v[170:171], v[120:121]
	s_waitcnt vmcnt(6)
	v_pk_fma_f32 v[22:23], v[230:231], v[112:113], v[22:23]
	v_pk_fma_f32 v[24:25], v[232:233], v[114:115], v[24:25]
	v_lshl_add_u64 v[116:117], v[34:35], 0, v[84:85]
	s_waitcnt vmcnt(5)
	v_pk_mul_f32 v[36:37], v[172:173], v[36:37]
	v_pk_mul_f32 v[38:39], v[174:175], v[40:41]
	s_waitcnt vmcnt(4)
	v_pk_fma_f32 v[14:15], v[234:235], v[36:37], v[14:15]
	v_pk_fma_f32 v[16:17], v[236:237], v[38:39], v[16:17]
	v_lshl_add_u64 v[40:41], v[34:35], 0, v[82:83]
	v_mov_b32_e32 v40, v106
	v_mov_b32_e32 v41, v104
	v_pk_mul_f32 v[40:41], v[40:41], v[108:109] op_sel_hi:[1,0]
	v_mov_b32_e32 v114, v102
	v_mov_b32_e32 v115, v100
	v_pk_mul_f32 v[114:115], v[114:115], v[108:109] op_sel_hi:[1,0]
	v_lshl_add_u64 v[34:35], v[34:35], 0, v[80:81]
	v_mov_b32_e32 v104, v107
	v_mov_b32_e32 v100, v103
	v_pk_mul_f32 v[104:105], v[104:105], v[108:109] op_sel_hi:[1,0]
	v_pk_mul_f32 v[100:101], v[100:101], v[108:109] op_sel_hi:[1,0]
	s_waitcnt vmcnt(3)
	v_pk_mul_f32 v[38:39], v[178:179], v[40:41]
	v_pk_mul_f32 v[36:37], v[176:177], v[114:115]
	s_waitcnt vmcnt(2)
	v_pk_fma_f32 v[12:13], v[240:241], v[38:39], v[12:13]
	v_pk_fma_f32 v[10:11], v[238:239], v[36:37], v[10:11]
	s_waitcnt vmcnt(1)
	v_pk_mul_f32 v[38:39], v[180:181], v[100:101]
	v_pk_mul_f32 v[40:41], v[182:183], v[104:105]
	s_waitcnt vmcnt(0)
	v_pk_fma_f32 v[2:3], v[242:243], v[38:39], v[2:3]
	v_pk_fma_f32 v[4:5], v[244:245], v[40:41], v[4:5]
	s_cbranch_vccnz .LBB0_1135
	global_store_dwordx4 v[88:89], v[6:9], off
	global_store_dwordx4 v[88:89], v[18:21], off offset:1024
	global_store_dwordx4 v[88:89], v[26:29], off offset:2048
	global_store_dwordx4 v[88:89], v[30:33], off offset:3072
	global_store_dwordx4 v[90:91], v[22:25], off
	global_store_dwordx4 v[92:93], v[14:17], off
	global_store_dwordx4 v[94:95], v[10:13], off
	global_store_dwordx4 v[96:97], v[2:5], off
; __device__ __forceinline__ unsigned pk2(float lo, float hi) { return pg8::cvt_pk_bf16(lo, hi); }
; __device__ __forceinline__ void row_pass(const RowPass& rp) {
;     ...
;         if (rp.h) {
;             float ss = 0.f;
; #pragma unroll
;             for (int j = 0; j < 8; ++j) ss += x[j][0] * x[j][0] + x[j][1] * x[j][1] + x[j][2] * x[j][2] + x[j][3] * x[j][3];
;             const float rstd = rsqrtf(wave_sum(ss) * (1.f / D) + EPS);
;             bf16_t* hr = rp.h + (size_t)row * D;
; #pragma unroll
;             for (int j = 0; j < 8; ++j) { const int col = 4 * (lane + 64 * j); const f32x4 gp = *(const f32x4*)(rp.gpre + col); const f32x4 sh = *(const f32x4*)(rp.shv + v * 12288 + col); const f32x4 sc = *(const f32x4*)(rp.scv + v * 12288 + col);
;                 const f32x4 y = (x[j] * rstd * gp) * (sc + 1.f) + sh; u32x2 w; w.x = pk2(y[0], y[1]); w.y = pk2(y[2], y[3]); *(u32x2*)(hr + col) = w; }
.LBB0_1135:
	s_andn2_b64 vcc, exec, s[14:15]
	s_cbranch_vccnz .LBB0_1132
	v_lshlrev_b64 v[250:251], 2, v[98:99]
	v_lshl_add_u64 v[144:145], s[0:1], 0, v[250:251]
	v_lshl_add_u64 v[146:147], s[4:5], 0, v[250:251]
	v_lshl_add_u64 v[246:247], v[144:145], 0, v[0:1]
	v_lshl_add_u64 v[248:249], v[146:147], 0, v[0:1]
	global_load_dwordx4 v[152:155], v[64:65], off offset:1024
	global_load_dwordx4 v[156:159], v[246:247], off offset:1024
	global_load_dwordx4 v[160:163], v[248:249], off offset:1024
	global_load_dwordx4 v[164:167], v[64:65], off offset:2048
	global_load_dwordx4 v[168:171], v[246:247], off offset:2048
	global_load_dwordx4 v[172:175], v[248:249], off offset:2048
	global_load_dwordx4 v[176:179], v[64:65], off offset:3072
	global_load_dwordx4 v[180:183], v[246:247], off offset:3072
	global_load_dwordx4 v[214:217], v[248:249], off offset:3072
	v_lshl_add_u64 v[250:251], v[144:145], 0, v[86:87]
	global_load_dwordx4 v[218:221], v[250:251], off
	global_load_dwordx4 v[222:225], v[66:67], off
	v_lshl_add_u64 v[250:251], v[146:147], 0, v[86:87]
	global_load_dwordx4 v[226:229], v[250:251], off
	v_lshl_add_u64 v[250:251], v[144:145], 0, v[84:85]
	global_load_dwordx4 v[230:233], v[250:251], off
	global_load_dwordx4 v[234:237], v[68:69], off
	v_lshl_add_u64 v[250:251], v[146:147], 0, v[84:85]
	global_load_dwordx4 v[238:241], v[250:251], off
	v_lshl_add_u64 v[250:251], v[144:145], 0, v[82:83]
	global_load_dwordx4 v[242:245], v[250:251], off
	global_load_dwordx4 v[184:187], v[70:71], off
	v_lshl_add_u64 v[250:251], v[146:147], 0, v[82:83]
	global_load_dwordx4 v[144:147], v[250:251], off
	v_mul_f32_e32 v34, v7, v7
	v_mul_f32_e32 v35, v19, v19
	v_fmac_f32_e32 v34, v6, v6
	v_fmac_f32_e32 v35, v18, v18
	v_fmac_f32_e32 v34, v8, v8
	v_fmac_f32_e32 v35, v20, v20
	v_fmac_f32_e32 v34, v9, v9
	v_fmac_f32_e32 v35, v21, v21
	v_add_f32_e32 v34, v34, v35
	v_mul_f32_e32 v35, v27, v27
	v_fmac_f32_e32 v35, v26, v26
	v_fmac_f32_e32 v35, v28, v28
	v_fmac_f32_e32 v35, v29, v29
	v_add_f32_e32 v34, v35, v34
	v_mul_f32_e32 v35, v31, v31
	v_fmac_f32_e32 v35, v30, v30
	v_fmac_f32_e32 v35, v32, v32
	v_fmac_f32_e32 v35, v33, v33
	v_mov_b32_e32 v36, v15
	v_mov_b32_e32 v37, v23
	v_add_f32_e32 v38, v35, v34
	v_mov_b32_e32 v34, v14
	v_mov_b32_e32 v35, v22
	v_pk_mul_f32 v[36:37], v[36:37], v[36:37]
	v_mov_b32_e32 v88, v0
	v_pk_fma_f32 v[34:35], v[34:35], v[34:35], v[36:37]
	v_mov_b32_e32 v36, v16
	v_mov_b32_e32 v37, v24
	v_pk_fma_f32 v[34:35], v[36:37], v[36:37], v[34:35]
	v_mov_b32_e32 v36, v17
	v_mov_b32_e32 v37, v25
	v_pk_fma_f32 v[34:35], v[36:37], v[36:37], v[34:35]
	v_mov_b32_e32 v36, v3
	v_add_f32_e32 v35, v35, v38
	v_mov_b32_e32 v37, v11
	v_add_f32_e32 v38, v34, v35
	v_mov_b32_e32 v34, v2
	v_mov_b32_e32 v35, v10
	v_pk_mul_f32 v[36:37], v[36:37], v[36:37]
	v_mov_b32_e32 v89, v1
	v_pk_fma_f32 v[34:35], v[34:35], v[34:35], v[36:37]
	v_mov_b32_e32 v36, v4
	v_mov_b32_e32 v37, v12
	v_pk_fma_f32 v[34:35], v[36:37], v[36:37], v[34:35]
	v_mov_b32_e32 v36, v5
	v_mov_b32_e32 v37, v13
	v_pk_fma_f32 v[34:35], v[36:37], v[36:37], v[34:35]
	v_lshlrev_b64 v[36:37], 2, v[98:99]
	v_add_f32_e32 v35, v35, v38
	v_lshl_add_u64 v[38:39], s[0:1], 0, v[36:37]
	v_lshl_add_u64 v[36:37], s[4:5], 0, v[36:37]
	v_lshl_add_u64 v[40:41], v[38:39], 0, v[88:89]
	v_lshl_add_u64 v[88:89], v[36:37], 0, v[88:89]
	global_load_dwordx4 v[90:93], v[64:65], off
	global_load_dwordx4 v[98:101], v[88:89], off
	global_load_dwordx4 v[94:97], v[40:41], off
	v_add_f32_e32 v34, v34, v35
	ds_bpermute_b32 v35, v45, v34
	v_mov_b32_e32 v87, v1
	v_mov_b32_e32 v85, v1
	v_mov_b32_e32 v83, v1
	v_mov_b32_e32 v81, v1
	s_waitcnt lgkmcnt(0)
	v_add_f32_e32 v34, v34, v35
	ds_bpermute_b32 v35, v47, v34
	s_waitcnt lgkmcnt(0)
	v_add_f32_e32 v34, v34, v35
	ds_bpermute_b32 v35, v49, v34
	s_waitcnt lgkmcnt(0)
	v_add_f32_e32 v34, v34, v35
	ds_bpermute_b32 v35, v51, v34
	s_waitcnt lgkmcnt(0)
	v_add_f32_e32 v34, v34, v35
	ds_bpermute_b32 v35, v53, v34
	s_waitcnt lgkmcnt(0)
	v_add_f32_e32 v34, v34, v35
	ds_bpermute_b32 v35, v109, v34
	s_waitcnt lgkmcnt(0)
	v_add_f32_e32 v34, v34, v35
	v_fmamk_f32 v34, v34, 0x3a000000, v197
	v_cmp_gt_f32_e32 vcc, s69, v34
	v_mul_f32_e32 v35, 0x4b800000, v34
	s_nop 0
	v_cndmask_b32_e32 v34, v34, v35, vcc
	v_rsq_f32_e32 v34, v34
	s_nop 0
	v_mul_f32_e32 v35, 0x45800000, v34
	v_cndmask_b32_e32 v34, v34, v35, vcc
	v_pk_mul_f32 v[8:9], v[8:9], v[34:35] op_sel_hi:[1,0]
	v_pk_mul_f32 v[6:7], v[6:7], v[34:35] op_sel_hi:[1,0]
	v_pk_mul_f32 v[18:19], v[18:19], v[34:35] op_sel_hi:[1,0]
	v_pk_mul_f32 v[26:27], v[26:27], v[34:35] op_sel_hi:[1,0]
	v_pk_mul_f32 v[30:31], v[30:31], v[34:35] op_sel_hi:[1,0]
	v_pk_mul_f32 v[22:23], v[22:23], v[34:35] op_sel_hi:[1,0]
	v_pk_mul_f32 v[14:15], v[14:15], v[34:35] op_sel_hi:[1,0]
	v_pk_mul_f32 v[10:11], v[10:11], v[34:35] op_sel_hi:[1,0]
	v_pk_mul_f32 v[4:5], v[4:5], v[34:35] op_sel_hi:[1,0]
	v_pk_mul_f32 v[2:3], v[2:3], v[34:35] op_sel_hi:[1,0]
	s_waitcnt vmcnt(2)
; __device__ __forceinline__ unsigned pk2(float lo, float hi) { return pg8::cvt_pk_bf16(lo, hi); }
; __device__ __forceinline__ void row_pass(const RowPass& rp) {
;     ...
; #pragma unroll
;             for (int j = 0; j < 8; ++j) { const int col = 4 * (lane + 64 * j); const f32x4 gp = *(const f32x4*)(rp.gpre + col); const f32x4 sh = *(const f32x4*)(rp.shv + v * 12288 + col); const f32x4 sc = *(const f32x4*)(rp.scv + v * 12288 + col);
;                 const f32x4 y = (x[j] * rstd * gp) * (sc + 1.f) + sh; u32x2 w; w.x = pk2(y[0], y[1]); w.y = pk2(y[2], y[3]); *(u32x2*)(hr + col) = w; }
	v_pk_mul_f32 v[6:7], v[90:91], v[6:7]
	v_pk_mul_f32 v[8:9], v[92:93], v[8:9]
	s_waitcnt vmcnt(1)
	v_pk_add_f32 v[90:91], v[100:101], 1.0 op_sel_hi:[1,0]
	v_pk_add_f32 v[92:93], v[98:99], 1.0 op_sel_hi:[1,0]
	s_waitcnt vmcnt(0)
	v_pk_fma_f32 v[8:9], v[90:91], v[8:9], v[96:97]
	v_pk_fma_f32 v[6:7], v[92:93], v[6:7], v[94:95]
	v_cvt_pk_bf16_f32 v91, v8, v9
	v_cvt_pk_bf16_f32 v90, v6, v7
	v_lshl_add_u64 v[6:7], v[76:77], 0, v[74:75]
	global_store_dwordx2 v[6:7], v[90:91], off
	s_nop 0
	v_pk_mul_f32 v[8:9], v[20:21], v[34:35] op_sel_hi:[1,0]
	v_pk_mul_f32 v[18:19], v[152:153], v[18:19]
	v_pk_mul_f32 v[8:9], v[154:155], v[8:9]
	v_pk_add_f32 v[20:21], v[162:163], 1.0 op_sel_hi:[1,0]
	v_pk_add_f32 v[90:91], v[160:161], 1.0 op_sel_hi:[1,0]
	v_pk_fma_f32 v[8:9], v[20:21], v[8:9], v[158:159]
	v_pk_fma_f32 v[18:19], v[90:91], v[18:19], v[156:157]
	s_nop 0
	v_cvt_pk_bf16_f32 v18, v18, v19
	v_cvt_pk_bf16_f32 v19, v8, v9
	global_store_dwordx2 v[6:7], v[18:19], off offset:512
	s_nop 0
	v_pk_mul_f32 v[8:9], v[28:29], v[34:35] op_sel_hi:[1,0]
	v_pk_mul_f32 v[18:19], v[164:165], v[26:27]
	v_pk_mul_f32 v[8:9], v[166:167], v[8:9]
	v_pk_add_f32 v[20:21], v[174:175], 1.0 op_sel_hi:[1,0]
	v_pk_add_f32 v[26:27], v[172:173], 1.0 op_sel_hi:[1,0]
	v_pk_fma_f32 v[8:9], v[20:21], v[8:9], v[170:171]
	v_pk_fma_f32 v[18:19], v[26:27], v[18:19], v[168:169]
	s_nop 0
	v_cvt_pk_bf16_f32 v18, v18, v19
	v_cvt_pk_bf16_f32 v19, v8, v9
	global_store_dwordx2 v[6:7], v[18:19], off offset:1024
	s_nop 0
	s_nop 0
	v_pk_mul_f32 v[8:9], v[32:33], v[34:35] op_sel_hi:[1,0]
	v_pk_mul_f32 v[18:19], v[30:31], v[176:177]
	v_pk_mul_f32 v[8:9], v[8:9], v[178:179]
	v_pk_add_f32 v[20:21], v[216:217], 1.0 op_sel_hi:[1,0]
	v_pk_add_f32 v[30:31], v[214:215], 1.0 op_sel_hi:[1,0]
	v_pk_fma_f32 v[8:9], v[8:9], v[20:21], v[182:183]
	v_pk_fma_f32 v[18:19], v[18:19], v[30:31], v[180:181]
	s_nop 0
	v_cvt_pk_bf16_f32 v18, v18, v19
	v_cvt_pk_bf16_f32 v19, v8, v9
	global_store_dwordx2 v[6:7], v[18:19], off offset:1536
	v_lshl_add_u64 v[8:9], v[38:39], 0, v[86:87]
	v_lshl_add_u64 v[8:9], v[36:37], 0, v[86:87]
	v_pk_mul_f32 v[8:9], v[24:25], v[34:35] op_sel_hi:[1,0]
	v_pk_mul_f32 v[18:19], v[22:23], v[222:223]
	v_pk_mul_f32 v[8:9], v[8:9], v[224:225]
	v_pk_add_f32 v[20:21], v[228:229], 1.0 op_sel_hi:[1,0]
	v_pk_add_f32 v[22:23], v[226:227], 1.0 op_sel_hi:[1,0]
	v_pk_fma_f32 v[8:9], v[8:9], v[20:21], v[220:221]
	v_pk_fma_f32 v[18:19], v[18:19], v[22:23], v[218:219]
	s_nop 0
	v_cvt_pk_bf16_f32 v18, v18, v19
	v_cvt_pk_bf16_f32 v19, v8, v9
	global_store_dwordx2 v[6:7], v[18:19], off offset:2048
	v_lshl_add_u64 v[8:9], v[38:39], 0, v[84:85]
	v_lshl_add_u64 v[8:9], v[36:37], 0, v[84:85]
	v_pk_mul_f32 v[8:9], v[16:17], v[34:35] op_sel_hi:[1,0]
	v_pk_mul_f32 v[14:15], v[14:15], v[234:235]
	v_pk_mul_f32 v[8:9], v[8:9], v[236:237]
	v_pk_add_f32 v[16:17], v[240:241], 1.0 op_sel_hi:[1,0]
	v_pk_add_f32 v[18:19], v[238:239], 1.0 op_sel_hi:[1,0]
	v_pk_fma_f32 v[8:9], v[8:9], v[16:17], v[232:233]
	v_pk_fma_f32 v[14:15], v[14:15], v[18:19], v[230:231]
	s_nop 0
	v_cvt_pk_bf16_f32 v14, v14, v15
	v_cvt_pk_bf16_f32 v15, v8, v9
	global_store_dwordx2 v[6:7], v[14:15], off offset:2560
	v_lshl_add_u64 v[8:9], v[38:39], 0, v[82:83]
	v_lshl_add_u64 v[8:9], v[36:37], 0, v[82:83]
	v_pk_mul_f32 v[8:9], v[12:13], v[34:35] op_sel_hi:[1,0]
	v_pk_mul_f32 v[10:11], v[10:11], v[184:185]
	v_pk_mul_f32 v[8:9], v[8:9], v[186:187]
	v_pk_add_f32 v[12:13], v[146:147], 1.0 op_sel_hi:[1,0]
	v_pk_add_f32 v[14:15], v[144:145], 1.0 op_sel_hi:[1,0]
	v_pk_fma_f32 v[8:9], v[8:9], v[12:13], v[244:245]
	v_pk_fma_f32 v[10:11], v[10:11], v[14:15], v[242:243]
	v_lshl_add_u64 v[16:17], v[36:37], 0, v[80:81]
	v_cvt_pk_bf16_f32 v10, v10, v11
	v_cvt_pk_bf16_f32 v11, v8, v9
	global_store_dwordx2 v[6:7], v[10:11], off offset:3072
	global_load_dwordx4 v[8:11], v[72:73], off
	v_lshl_add_u64 v[12:13], v[38:39], 0, v[80:81]
	global_load_dwordx4 v[16:19], v[16:17], off
	s_waitcnt vmcnt(1)
	v_pk_mul_f32 v[2:3], v[2:3], v[8:9]
	global_load_dwordx4 v[12:15], v[12:13], off
	v_pk_mul_f32 v[4:5], v[4:5], v[10:11]
	s_waitcnt vmcnt(1)
	v_pk_add_f32 v[8:9], v[18:19], 1.0 op_sel_hi:[1,0]
	v_pk_add_f32 v[10:11], v[16:17], 1.0 op_sel_hi:[1,0]
	s_waitcnt vmcnt(0)
	v_pk_fma_f32 v[4:5], v[4:5], v[8:9], v[14:15]
	v_pk_fma_f32 v[2:3], v[2:3], v[10:11], v[12:13]
	s_nop 0
	v_cvt_pk_bf16_f32 v2, v2, v3
	v_cvt_pk_bf16_f32 v3, v4, v5
	global_store_dwordx2 v[6:7], v[2:3], off offset:3584
	s_branch .LBB0_1132
